# pool-GEMM phase 14: LDS-DMA core (nk=8) + custom LDS-transposed epilogue (coalesced gate tile load, silu via exp/rcp+Newton in f32, coalesced bf16 stores)
# speedup vs baseline: 1.0374x; 1.0269x over previous
; #define GA_LOAD(pr_) do { _Pragma("unroll") for (int i = 0; i < 4; ++i) ra[i] = *(const u32x4*)(Ab + (i * 32) * lda + (pr_) * 64); } while (0)
; #define GB_LOAD(kt_) do { const bfr* bk_ = Bb + (kt_) * NB * 32; \
;     _Pragma("unroll") for (int i = 0; i < 4; ++i) rb[i] = *(const u32x4*)(bk_ + (i * 64) * 32); } while (0)
; #define G_STORE(kt_) do { bfr* as_ = S0 + ((kt_) & 1) * GSTAGE; bfr* bs_ = as_ + 128 * 40; \
;     if (apar == ((kt_) & 1)) { _Pragma("unroll") for (int i = 0; i < 4; ++i) *(u32x4*)(as_ + asoff + i * 32 * 40) = ra[i]; } \
;     _Pragma("unroll") for (int i = 0; i < 4; ++i) *(u32x4*)(bs_ + bsoff + i * 64 * 40) = rb[i]; } while (0)
; template <int lda>
; DI void gemm_mainloop(const bfr* __restrict__ A, const bfr* __restrict__ Bt, int NB, int K, int m0, int n0, char* smem, f32x16 (&acc)[2][4]) {
;   bfr* S0 = (bfr*)smem;
;   int tid = threadIdx.x;
;   asm volatile("" : "+v"(tid));
;   const int lane = tid & 63, wid = tid >> 6, wr = wid >> 1, wc = wid & 1;
;   const int r = lane & 31, hl = lane >> 5;
; #pragma unroll
;   for (int i = 0; i < 2; ++i)
; #pragma unroll
;     for (int j = 0; j < 4; ++j)
; #pragma unroll
;       for (int q = 0; q < 16; ++q) acc[i][j][q] = 0.f;
;   u32x4 ra[4], rb[4];
;   const int nk = K >> 5;
;   const int arow = tid >> 3, ac8 = tid & 7, apar = ac8 >> 2;
;   const bfr* Ab = A + (m0 + arow) * lda + ac8 * 8;
;   const int asoff = arow * 40 + (ac8 & 3) * 8;
;   const int brow = tid >> 2, bc4 = tid & 3;
;   const bfr* Bb = Bt + (n0 + brow) * 32 + bc4 * 8;
;   const int bsoff = brow * 40 + bc4 * 8;
;     ...
;   GA_LOAD(0);
;   GB_LOAD(0);
;   G_STORE(0);
;   GB_LOAD(1);
;   __syncthreads();
;   for (int kt = 0; kt < nk; ++kt) {
;     if (kt + 1 < nk) G_STORE(kt + 1);
;     if (kt + 2 < nk) {
;       GB_LOAD(kt + 2);
;       if ((kt & 1) == 0) GA_LOAD((kt >> 1) + 1);
;     }
; DI void phase_gemm_pool(const Params& p, char* smem) {
;     ...
;   for (int t0 = blockIdx.x; t0 < 128 * 4; t0 += gridDim.x) {
;     const int t = ((gridDim.x & 7) == 0) ? xcd_tile(t0, 4) : t0;
;     int mt = t >> 2, g = t & 3, nt = 0;
;     const float* bp = p.b_pool + g * 256;
;     const float* sc = p.pool_scale + g * 256;
;     gemm_tile<1024>(p.MIX + g * 256, p.WtPool + (size_t)g * 65536, 256, 256, mt * 128, nt * 256, smem,
.LBB0_1374:
	s_cmpk_gt_i32 s46, 0x1ff
	s_cbranch_scc1 .LBB0_1395
	v_readlane_b32 s0, v254, 0
	v_readlane_b32 s1, v254, 1
	s_load_dword s0, s[0:1], 0x10
	s_mov_b32 s11, 0
	s_load_dwordx2 s[20:21], s[92:93], 0x158
	v_mov_b32_e32 v161, 0
	s_mov_b32 s27, 0x10000
	s_waitcnt lgkmcnt(0)
	s_lshr_b32 s0, s0, 16
	s_cmp_lg_u32 s0, 0
	s_cselect_b64 s[0:1], -1, 0
	s_cmp_lg_u64 s[0:1], 0
	s_addc_u32 s24, s34, 0
	s_and_b32 s0, s24, 7
	s_cmp_eq_u32 s0, 0
	s_cselect_b64 s[0:1], -1, 0
	v_cndmask_b32_e64 v0, 0, 1, s[0:1]
	s_lshl_b32 s25, s46, 4
	s_lshl_b32 s26, s24, 4
	v_cmp_ne_u32_e64 s[0:1], 1, v0
	s_mov_b32 s28, 0x20000
	s_mov_b32 s29, 0x30000
	s_movk_i32 s30, 0x1000
	s_mov_b32 s31, 0xfffffc0
	s_movk_i32 s33, 0x80
	s_movk_i32 s36, 0x50
	s_mov_b32 s37, s46
	s_branch .LBB0_1377
.LBB0_1377:
	s_and_b64 vcc, exec, s[0:1]
	s_mov_b32 s4, s37
	s_cbranch_vccnz .LBB0_1379
	s_ashr_i32 s4, s37, 3
	s_lshr_b32 s6, s4, 30
	s_add_i32 s6, s4, s6
	s_and_b32 s5, s25, 0x70
	s_lshr_b32 s7, s6, 2
	s_add_i32 s7, s7, s5
	s_and_b32 s6, s6, -4
	s_lshl_b32 s5, s7, 2
	s_sub_i32 s4, s4, s6
	s_add_i32 s4, s5, s4
.LBB0_1379:
	s_and_b32 s38, s4, 3
	s_lshl_b32 s5, s38, 9
	s_add_u32 s6, s20, s5
	s_addc_u32 s7, s21, 0
	s_lshl_b32 s5, s38, 17
	s_add_u32 s22, s18, s5
	s_addc_u32 s23, s19, 0
	s_lshl_b32 s4, s4, 5
	s_and_b32 s10, s4, 0xffffff80
	s_lshl_b32 s98, s10, 11
	s_add_u32 s98, s6, s98
	s_addc_u32 s99, s7, 0
	s_lshl_b32 s100, 0, 6
	s_add_u32 s100, s22, s100
	s_addc_u32 s101, s23, 0
	v_writelane_b32 v188, s64, 0
	v_writelane_b32 v188, s65, 1
	v_writelane_b32 v188, s66, 2
	v_writelane_b32 v188, s67, 3
	v_writelane_b32 v188, s68, 4
	v_writelane_b32 v188, s69, 5
	v_writelane_b32 v188, s70, 6
	v_writelane_b32 v188, s71, 7
	v_writelane_b32 v188, s72, 8
	v_writelane_b32 v188, s73, 9
	v_writelane_b32 v188, s74, 10
	v_writelane_b32 v188, s75, 11
	v_writelane_b32 v188, s76, 12
	v_writelane_b32 v188, s77, 13
	v_writelane_b32 v188, s78, 14
	v_writelane_b32 v188, s79, 15
	s_mov_b32 s77, s10
	s_mov_b32 s78, 0
	s_lshl_b32 s78, s38, 8
	v_lshrrev_b32_e32 v189, 6, v196
	v_and_b32_e32 v190, 63, v196
	v_readfirstlane_b32 s73, v189
	v_lshrrev_b32_e32 v191, 2, v190
	v_bfe_u32 v192, v190, 4, 2
	v_and_b32_e32 v189, 3, v190
	v_xor_b32_e32 v189, v189, v192
	v_lshlrev_b32_e32 v189, 4, v189
	v_lshl_add_u32 v160, v191, 11, v189
	v_add_u32_e32 v162, 0x8000, v160
	v_lshl_add_u32 v163, v191, 6, v189
	v_and_b32_e32 v191, 31, v190
	v_lshrrev_b32_e32 v192, 5, v190
	v_bfe_u32 v189, v190, 2, 2
	v_xor_b32_e32 v189, v189, v192
	v_lshlrev_b32_e32 v189, 4, v189
	v_lshl_add_u32 v180, v191, 6, v189
	s_lshr_b32 s74, s73, 1
	s_lshl_b32 s74, s74, 12
	s_and_b32 s75, s73, 1
	s_lshl_b32 s75, s75, 13
	v_add_u32_e32 v182, s75, v180
	v_add_u32_e32 v180, s74, v180
	v_xor_b32_e32 v183, 32, v182
	v_xor_b32_e32 v181, 32, v180
	s_lshl_b32 s74, s73, 16
	s_add_u32 s64, s98, s74
	s_addc_u32 s65, s99, 0
	s_lshl_b32 s74, s73, 12
	s_add_u32 s66, s100, s74
	s_addc_u32 s67, s101, 0
	s_lshl_b32 s68, s73, 11
	s_lshl_b32 s69, s73, 12
	s_mov_b32 s70, 0
	s_mov_b32 s71, 0
	s_mov_b32 s72, 0
	s_waitcnt lgkmcnt(0)
	s_barrier
	s_mul_i32 s74, s70, 0x6000
	s_add_u32 s75, s74, s68
	s_mov_b32 m0, s75
	s_add_u32 s76, s74, 0x2000
	s_cmp_eq_u32 s70, 2
	s_cselect_b32 s76, 0x10000, s76
	global_load_lds_dwordx4 v160, s[64:65]
	s_add_u32 m0, s75, 0x400
	s_add_u32 s76, s76, s69
	global_load_lds_dwordx4 v162, s[64:65]
	s_mov_b32 m0, s76
	s_add_u32 s64, s64, 64
	s_addc_u32 s65, s65, 0
	global_load_lds_dwordx4 v163, s[66:67]
	global_load_lds_dwordx4 v163, s[66:67] offset:1024
	global_load_lds_dwordx4 v163, s[66:67] offset:2048
	global_load_lds_dwordx4 v163, s[66:67] offset:3072
	s_add_u32 s66, s66, 0x4000
	s_addc_u32 s67, s67, 0
	s_add_u32 s70, s70, 1
	s_cmp_eq_u32 s70, 3
	s_cselect_b32 s70, 0, s70
	s_mul_i32 s74, s70, 0x6000
	s_add_u32 s75, s74, s68
	s_mov_b32 m0, s75
	s_add_u32 s76, s74, 0x2000
	s_cmp_eq_u32 s70, 2
	s_cselect_b32 s76, 0x10000, s76
	global_load_lds_dwordx4 v160, s[64:65]
	s_add_u32 m0, s75, 0x400
	s_add_u32 s76, s76, s69
	global_load_lds_dwordx4 v162, s[64:65]
	s_mov_b32 m0, s76
	s_add_u32 s64, s64, 64
	s_addc_u32 s65, s65, 0
	global_load_lds_dwordx4 v163, s[66:67]
	global_load_lds_dwordx4 v163, s[66:67] offset:1024
	global_load_lds_dwordx4 v163, s[66:67] offset:2048
	global_load_lds_dwordx4 v163, s[66:67] offset:3072
	s_add_u32 s66, s66, 0x4000
	s_addc_u32 s67, s67, 0
	s_add_u32 s70, s70, 1
	s_cmp_eq_u32 s70, 3
	s_cselect_b32 s70, 0, s70
	s_cmp_lt_u32 s46, 0x100
	s_cbranch_scc1 .Lp14_nostag
	s_sleep 8

; #define MFMA32(a, b, c) __builtin_amdgcn_mfma_f32_32x32x16_bf16((a), (b), (c), 0, 0, 0)
; #define GA_LOAD(pr_) do { _Pragma("unroll") for (int i = 0; i < 4; ++i) ra[i] = *(const u32x4*)(Ab + (i * 32) * lda + (pr_) * 64); } while (0)
; #define GB_LOAD(kt_) do { const bfr* bk_ = Bb + (kt_) * NB * 32; \
;     _Pragma("unroll") for (int i = 0; i < 4; ++i) rb[i] = *(const u32x4*)(bk_ + (i * 64) * 32); } while (0)
; #define G_STORE(kt_) do { bfr* as_ = S0 + ((kt_) & 1) * GSTAGE; bfr* bs_ = as_ + 128 * 40; \
;     if (apar == ((kt_) & 1)) { _Pragma("unroll") for (int i = 0; i < 4; ++i) *(u32x4*)(as_ + asoff + i * 32 * 40) = ra[i]; } \
;     _Pragma("unroll") for (int i = 0; i < 4; ++i) *(u32x4*)(bs_ + bsoff + i * 64 * 40) = rb[i]; } while (0)
; template <int lda>
; DI void gemm_mainloop(const bfr* __restrict__ A, const bfr* __restrict__ Bt, int NB, int K, int m0, int n0, char* smem, f32x16 (&acc)[2][4]) {
;     ...
;   for (int kt = 0; kt < nk; ++kt) {
;     if (kt + 1 < nk) G_STORE(kt + 1);
;     if (kt + 2 < nk) {
;       GB_LOAD(kt + 2);
;       if ((kt & 1) == 0) GA_LOAD((kt >> 1) + 1);
;     }
;     const bfr* As = S0 + (kt & 1) * GSTAGE;
;     const bfr* Bs = As + 128 * 40;
; #pragma unroll
;     for (int ks = 0; ks < 2; ++ks) {
;       bf16x8 af[2], bfg[4];
; #pragma unroll
;       for (int i = 0; i < 2; ++i) af[i] = *(const bf16x8*)(As + (wr * 64 + i * 32 + r) * 40 + ks * 16 + hl * 8);
; #pragma unroll
;       for (int j = 0; j < 4; ++j) bfg[j] = *(const bf16x8*)(Bs + (wc * 128 + j * 32 + r) * 40 + ks * 16 + hl * 8);
; #pragma unroll
;       for (int i = 0; i < 2; ++i)
; #pragma unroll
;         for (int j = 0; j < 4; ++j) acc[i][j] = MFMA32(af[i], bfg[j], acc[i][j]);
;     }
;     __syncthreads();
.Lp14_loop:
	s_waitcnt vmcnt(6)
	s_barrier
	s_mul_i32 s74, s71, 0x6000
	s_add_u32 s75, s74, 0x2000
	s_cmp_eq_u32 s71, 2
	s_cselect_b32 s75, 0x10000, s75
	v_add_u32_e32 v184, s74, v180
	v_add_u32_e32 v186, s75, v182
	v_add_u32_e32 v185, s74, v181
	v_add_u32_e32 v187, s75, v183
	ds_read_b128 v[128:131], v184
	ds_read_b128 v[144:147], v186
	ds_read_b128 v[148:151], v186 offset:2048
	ds_read_b128 v[152:155], v186 offset:4096
	ds_read_b128 v[156:159], v186 offset:6144
	ds_read_b128 v[132:135], v184 offset:2048
	ds_read_b128 v[136:139], v185
	ds_read_b128 v[164:167], v187
	ds_read_b128 v[168:171], v187 offset:2048
	ds_read_b128 v[172:175], v187 offset:4096
	ds_read_b128 v[176:179], v187 offset:6144
	ds_read_b128 v[140:143], v185 offset:2048
	s_add_u32 s71, s71, 1
	s_cmp_eq_u32 s71, 3
	s_cselect_b32 s71, 0, s71
	s_waitcnt lgkmcnt(10)
	v_mfma_f32_32x32x16_bf16 v[112:127], v[144:147], v[128:131], v[112:127]
	s_mul_i32 s74, s70, 0x6000
	s_add_u32 s75, s74, s68
	s_mov_b32 m0, s75
	s_add_u32 s76, s74, 0x2000
	s_cmp_eq_u32 s70, 2
	s_cselect_b32 s76, 0x10000, s76
	global_load_lds_dwordx4 v160, s[64:65]
	s_waitcnt lgkmcnt(9)
	v_mfma_f32_32x32x16_bf16 v[96:111], v[148:151], v[128:131], v[96:111]
	s_add_u32 m0, s75, 0x400
	s_add_u32 s76, s76, s69
	global_load_lds_dwordx4 v162, s[64:65]
	s_waitcnt lgkmcnt(8)
	v_mfma_f32_32x32x16_bf16 v[80:95], v[152:155], v[128:131], v[80:95]
	s_mov_b32 m0, s76
	s_add_u32 s64, s64, 64
	s_addc_u32 s65, s65, 0
	global_load_lds_dwordx4 v163, s[66:67]
	s_waitcnt lgkmcnt(7)
	v_mfma_f32_32x32x16_bf16 v[64:79], v[156:159], v[128:131], v[64:79]
	global_load_lds_dwordx4 v163, s[66:67] offset:1024
	s_waitcnt lgkmcnt(6)
	v_mfma_f32_32x32x16_bf16 v[48:63], v[144:147], v[132:135], v[48:63]
	global_load_lds_dwordx4 v163, s[66:67] offset:2048
	v_mfma_f32_32x32x16_bf16 v[32:47], v[148:151], v[132:135], v[32:47]
	global_load_lds_dwordx4 v163, s[66:67] offset:3072
	s_add_u32 s66, s66, 0x4000
	s_addc_u32 s67, s67, 0
	v_mfma_f32_32x32x16_bf16 v[16:31], v[152:155], v[132:135], v[16:31]
	s_add_u32 s70, s70, 1
	s_cmp_eq_u32 s70, 3
	s_cselect_b32 s70, 0, s70
	v_mfma_f32_32x32x16_bf16 v[0:15], v[156:159], v[132:135], v[0:15]
	s_waitcnt lgkmcnt(4)
	v_mfma_f32_32x32x16_bf16 v[112:127], v[164:167], v[136:139], v[112:127]
	s_waitcnt lgkmcnt(3)
	v_mfma_f32_32x32x16_bf16 v[96:111], v[168:171], v[136:139], v[96:111]
	s_waitcnt lgkmcnt(2)
	v_mfma_f32_32x32x16_bf16 v[80:95], v[172:175], v[136:139], v[80:95]
	s_waitcnt lgkmcnt(1)
	v_mfma_f32_32x32x16_bf16 v[64:79], v[176:179], v[136:139], v[64:79]
	s_waitcnt lgkmcnt(0)
	v_mfma_f32_32x32x16_bf16 v[48:63], v[164:167], v[140:143], v[48:63]
	v_mfma_f32_32x32x16_bf16 v[32:47], v[168:171], v[140:143], v[32:47]
	v_mfma_f32_32x32x16_bf16 v[16:31], v[172:175], v[140:143], v[16:31]
	v_mfma_f32_32x32x16_bf16 v[0:15], v[176:179], v[140:143], v[0:15]
	s_add_u32 s72, s72, 1
	s_cmp_lt_u32 s72, 6
	s_cbranch_scc1 .Lp14_loop
	s_waitcnt vmcnt(6)
	s_barrier
	s_mul_i32 s74, s71, 0x6000
	s_add_u32 s75, s74, 0x2000
	s_cmp_eq_u32 s71, 2
	s_cselect_b32 s75, 0x10000, s75
	v_add_u32_e32 v184, s74, v180
	v_add_u32_e32 v186, s75, v182
	v_add_u32_e32 v185, s74, v181
	v_add_u32_e32 v187, s75, v183
	ds_read_b128 v[128:131], v184
	ds_read_b128 v[144:147], v186
	ds_read_b128 v[148:151], v186 offset:2048
	ds_read_b128 v[152:155], v186 offset:4096
	ds_read_b128 v[156:159], v186 offset:6144
	ds_read_b128 v[132:135], v184 offset:2048
	ds_read_b128 v[136:139], v185
	ds_read_b128 v[164:167], v187
	ds_read_b128 v[168:171], v187 offset:2048
	ds_read_b128 v[172:175], v187 offset:4096
	ds_read_b128 v[176:179], v187 offset:6144
	ds_read_b128 v[140:143], v185 offset:2048
	s_add_u32 s71, s71, 1
	s_cmp_eq_u32 s71, 3
	s_cselect_b32 s71, 0, s71
	s_waitcnt lgkmcnt(10)
	v_mfma_f32_32x32x16_bf16 v[112:127], v[144:147], v[128:131], v[112:127]
	s_waitcnt lgkmcnt(9)
	v_mfma_f32_32x32x16_bf16 v[96:111], v[148:151], v[128:131], v[96:111]
	s_waitcnt lgkmcnt(8)
	v_mfma_f32_32x32x16_bf16 v[80:95], v[152:155], v[128:131], v[80:95]
	s_waitcnt lgkmcnt(7)
	v_mfma_f32_32x32x16_bf16 v[64:79], v[156:159], v[128:131], v[64:79]
	s_waitcnt lgkmcnt(6)
	v_mfma_f32_32x32x16_bf16 v[48:63], v[144:147], v[132:135], v[48:63]
	v_mfma_f32_32x32x16_bf16 v[32:47], v[148:151], v[132:135], v[32:47]
	v_mfma_f32_32x32x16_bf16 v[16:31], v[152:155], v[132:135], v[16:31]
	v_mfma_f32_32x32x16_bf16 v[0:15], v[156:159], v[132:135], v[0:15]
	s_waitcnt lgkmcnt(4)
	v_mfma_f32_32x32x16_bf16 v[112:127], v[164:167], v[136:139], v[112:127]
	s_waitcnt lgkmcnt(3)
	v_mfma_f32_32x32x16_bf16 v[96:111], v[168:171], v[136:139], v[96:111]
	s_waitcnt lgkmcnt(2)
	v_mfma_f32_32x32x16_bf16 v[80:95], v[172:175], v[136:139], v[80:95]
	s_waitcnt lgkmcnt(1)
	v_mfma_f32_32x32x16_bf16 v[64:79], v[176:179], v[136:139], v[64:79]
	s_waitcnt lgkmcnt(0)
	v_mfma_f32_32x32x16_bf16 v[48:63], v[164:167], v[140:143], v[48:63]
	v_mfma_f32_32x32x16_bf16 v[32:47], v[168:171], v[140:143], v[32:47]
	v_mfma_f32_32x32x16_bf16 v[16:31], v[172:175], v[140:143], v[16:31]
	v_mfma_f32_32x32x16_bf16 v[0:15], v[176:179], v[140:143], v[0:15]
	s_waitcnt vmcnt(0)
	s_barrier
; #define MFMA32(a, b, c) __builtin_amdgcn_mfma_f32_32x32x16_bf16((a), (b), (c), 0, 0, 0)
; DI bfr f2bf(float a) { return (bfr)(pack2(a, 0.f) & 0xffffu); }
; DI float bf2f(bfr u) { return __uint_as_float(((unsigned)u) << 16); }
; DI float siluf_(float x) { return x / (1.0f + __expf(-x)); }
; template <int lda>
; DI void gemm_mainloop(const bfr* __restrict__ A, const bfr* __restrict__ Bt, int NB, int K, int m0, int n0, char* smem, f32x16 (&acc)[2][4]) {
;     ...
; #pragma unroll
;     for (int ks = 0; ks < 2; ++ks) {
;       bf16x8 af[2], bfg[4];
; #pragma unroll
;       for (int i = 0; i < 2; ++i) af[i] = *(const bf16x8*)(As + (wr * 64 + i * 32 + r) * 40 + ks * 16 + hl * 8);
; #pragma unroll
;       for (int j = 0; j < 4; ++j) bfg[j] = *(const bf16x8*)(Bs + (wc * 128 + j * 32 + r) * 40 + ks * 16 + hl * 8);
; #pragma unroll
;       for (int i = 0; i < 2; ++i)
; #pragma unroll
;         for (int j = 0; j < 4; ++j) acc[i][j] = MFMA32(af[i], bfg[j], acc[i][j]);
; DI void phase_gemm_pool(const Params& p, char* smem) {
;     ...
;     gemm_tile<1024>(p.MIX + g * 256, p.WtPool + (size_t)g * 65536, 256, 256, mt * 128, nt * 256, smem,
;               [=](int row, int col, float v) {
;                 float gate = bf2f(P2[(size_t)row * 2048 + 1024 + g * 256 + col]);
;                 float z = (v + bp[col]) * sc[col] * siluf_(gate);
;                 Z[(size_t)row * 1024 + g * 256 + col] = f2bf(z);
;               });
	s_mul_i32 s74, s71, 0x6000
	s_add_u32 s75, s74, 0x2000
	s_cmp_eq_u32 s71, 2
	s_cselect_b32 s75, 0x10000, s75
	v_add_u32_e32 v184, s74, v180
	v_add_u32_e32 v186, s75, v182
	v_add_u32_e32 v185, s74, v181
	v_add_u32_e32 v187, s75, v183
	ds_read_b128 v[128:131], v184
	ds_read_b128 v[144:147], v186
	ds_read_b128 v[148:151], v186 offset:2048
	ds_read_b128 v[152:155], v186 offset:4096
	ds_read_b128 v[156:159], v186 offset:6144
	ds_read_b128 v[132:135], v184 offset:2048
	ds_read_b128 v[136:139], v185
	ds_read_b128 v[164:167], v187
	ds_read_b128 v[168:171], v187 offset:2048
	ds_read_b128 v[172:175], v187 offset:4096
	ds_read_b128 v[176:179], v187 offset:6144
	ds_read_b128 v[140:143], v185 offset:2048
	s_add_u32 s71, s71, 1
	s_cmp_eq_u32 s71, 3
	s_cselect_b32 s71, 0, s71
	s_waitcnt lgkmcnt(10)
	v_mfma_f32_32x32x16_bf16 v[112:127], v[144:147], v[128:131], v[112:127]
	s_waitcnt lgkmcnt(9)
	v_mfma_f32_32x32x16_bf16 v[96:111], v[148:151], v[128:131], v[96:111]
	s_waitcnt lgkmcnt(8)
	v_mfma_f32_32x32x16_bf16 v[80:95], v[152:155], v[128:131], v[80:95]
	s_waitcnt lgkmcnt(7)
	v_mfma_f32_32x32x16_bf16 v[64:79], v[156:159], v[128:131], v[64:79]
	s_waitcnt lgkmcnt(6)
	v_mfma_f32_32x32x16_bf16 v[48:63], v[144:147], v[132:135], v[48:63]
	v_mfma_f32_32x32x16_bf16 v[32:47], v[148:151], v[132:135], v[32:47]
	v_mfma_f32_32x32x16_bf16 v[16:31], v[152:155], v[132:135], v[16:31]
	v_mfma_f32_32x32x16_bf16 v[0:15], v[156:159], v[132:135], v[0:15]
	s_waitcnt lgkmcnt(4)
	v_mfma_f32_32x32x16_bf16 v[112:127], v[164:167], v[136:139], v[112:127]
	s_waitcnt lgkmcnt(3)
	v_mfma_f32_32x32x16_bf16 v[96:111], v[168:171], v[136:139], v[96:111]
	s_waitcnt lgkmcnt(2)
	v_mfma_f32_32x32x16_bf16 v[80:95], v[172:175], v[136:139], v[80:95]
	s_waitcnt lgkmcnt(1)
	v_mfma_f32_32x32x16_bf16 v[64:79], v[176:179], v[136:139], v[64:79]
	s_waitcnt lgkmcnt(0)
	v_mfma_f32_32x32x16_bf16 v[48:63], v[164:167], v[140:143], v[48:63]
	v_mfma_f32_32x32x16_bf16 v[32:47], v[168:171], v[140:143], v[32:47]
	v_mfma_f32_32x32x16_bf16 v[16:31], v[172:175], v[140:143], v[16:31]
	v_mfma_f32_32x32x16_bf16 v[0:15], v[176:179], v[140:143], v[0:15]
	s_nop 7
	s_nop 3
	s_load_dwordx2 s[64:65], s[92:93], 0x150
	s_load_dwordx2 s[66:67], s[92:93], 0x168
	s_load_dwordx4 s[68:71], s[92:93], 0xc0
	s_mul_i32 s76, s73, 8704
	s_lshr_b32 s74, s73, 1
	s_lshl_b32 s74, s74, 6
	s_add_u32 s74, s74, s77
	s_and_b32 s75, s73, 1
	s_lshl_b32 s75, s75, 7
	s_add_u32 s75, s75, s78
	v_and_b32_e32 v189, 31, v196
	v_bfe_u32 v190, v196, 5, 1
	v_mul_u32_u24_e32 v191, 272, v189
	v_add_u32_e32 v191, s76, v191
	v_lshl_add_u32 v160, v190, 3, v191
	v_lshlrev_b32_e32 v191, 2, v190
	v_add_lshl_u32 v181, v191, s75, 2
	v_bfe_u32 v189, v196, 4, 2
	v_and_b32_e32 v190, 15, v196
	v_mul_u32_u24_e32 v191, 272, v189
	v_lshl_add_u32 v191, v190, 4, v191
	v_add_u32_e32 v162, s76, v191
	v_add_u32_e32 v191, s74, v189
	v_lshlrev_b32_e32 v192, 3, v190
	v_add_u32_e32 v192, s75, v192
	v_lshl_add_u32 v189, v191, 10, v192
	v_lshlrev_b32_e32 v180, 1, v189
	v_add_u32_e32 v192, 0x400, v192
	v_lshl_add_u32 v189, v191, 11, v192
	v_lshlrev_b32_e32 v163, 1, v189
	s_waitcnt lgkmcnt(0)
	s_barrier
	s_add_u32 s74, s64, 0x0
	s_addc_u32 s75, s65, 0
	global_load_dwordx4 v[128:131], v163, s[74:75]
	s_add_u32 s74, s64, 0x4000
	s_addc_u32 s75, s65, 0
	global_load_dwordx4 v[132:135], v163, s[74:75]
	s_add_u32 s74, s64, 0x8000
	s_addc_u32 s75, s65, 0
	global_load_dwordx4 v[136:139], v163, s[74:75]
	s_add_u32 s74, s64, 0xc000
	s_addc_u32 s75, s65, 0
	global_load_dwordx4 v[140:143], v163, s[74:75]
	s_add_u32 s74, s64, 0x10000
	s_addc_u32 s75, s65, 0
	global_load_dwordx4 v[144:147], v163, s[74:75]
	s_add_u32 s74, s64, 0x14000
	s_addc_u32 s75, s65, 0
	global_load_dwordx4 v[148:151], v163, s[74:75]
	s_add_u32 s74, s64, 0x18000
	s_addc_u32 s75, s65, 0
	global_load_dwordx4 v[152:155], v163, s[74:75]
	s_add_u32 s74, s64, 0x1c000
	s_addc_u32 s75, s65, 0
	global_load_dwordx4 v[156:159], v163, s[74:75]
	s_waitcnt vmcnt(7)
	ds_write_b128 v162, v[128:131]
	s_waitcnt vmcnt(6)
	ds_write_b128 v162, v[132:135] offset:1088
	s_waitcnt vmcnt(5)
	ds_write_b128 v162, v[136:139] offset:2176
	s_waitcnt vmcnt(4)
	ds_write_b128 v162, v[140:143] offset:3264
	s_waitcnt vmcnt(3)
	ds_write_b128 v162, v[144:147] offset:4352
	s_waitcnt vmcnt(2)
	ds_write_b128 v162, v[148:151] offset:5440
	s_waitcnt vmcnt(1)
	ds_write_b128 v162, v[152:155] offset:6528
	s_waitcnt vmcnt(0)
	ds_write_b128 v162, v[156:159] offset:7616
	global_load_dwordx4 v[128:131], v181, s[68:69]
	global_load_dwordx4 v[132:135], v181, s[68:69] offset:32
	global_load_dwordx4 v[136:139], v181, s[68:69] offset:64
	global_load_dwordx4 v[140:143], v181, s[68:69] offset:96
	global_load_dwordx4 v[144:147], v181, s[70:71]
	global_load_dwordx4 v[148:151], v181, s[70:71] offset:32
	global_load_dwordx4 v[152:155], v181, s[70:71] offset:64
	global_load_dwordx4 v[156:159], v181, s[70:71] offset:96
	ds_read_b64 v[164:165], v160
	s_waitcnt vmcnt(3) lgkmcnt(0)
; DI bfr f2bf(float a) { return (bfr)(pack2(a, 0.f) & 0xffffu); }
; DI float bf2f(bfr u) { return __uint_as_float(((unsigned)u) << 16); }
; DI float siluf_(float x) { return x / (1.0f + __expf(-x)); }
; DI void phase_gemm_pool(const Params& p, char* smem) {
;     ...
;                 float gate = bf2f(P2[(size_t)row * 2048 + 1024 + g * 256 + col]);
;                 float z = (v + bp[col]) * sc[col] * siluf_(gate);
;                 Z[(size_t)row * 1024 + g * 256 + col] = f2bf(z);
	v_lshlrev_b32_e32 v182, 16, v164
	v_and_b32_e32 v183, 0xffff0000, v164
	v_lshlrev_b32_e32 v184, 16, v165
	v_and_b32_e32 v185, 0xffff0000, v165
	v_add_f32_e32 v112, v128, v112
	v_mul_f32_e32 v112, v144, v112
	v_add_f32_e32 v113, v129, v113
	v_mul_f32_e32 v113, v145, v113
	v_add_f32_e32 v114, v130, v114
	v_mul_f32_e32 v114, v146, v114
	v_add_f32_e32 v115, v131, v115
	v_mul_f32_e32 v115, v147, v115
	v_mul_f32_e32 v189, 0xbfb8aa3b, v182
	v_mul_f32_e32 v190, 0xbfb8aa3b, v183
	v_mul_f32_e32 v191, 0xbfb8aa3b, v184
	v_mul_f32_e32 v192, 0xbfb8aa3b, v185
	v_exp_f32_e32 v189, v189
	v_exp_f32_e32 v190, v190
	v_exp_f32_e32 v191, v191
	v_exp_f32_e32 v192, v192
	s_nop 0
	v_add_f32_e32 v189, 1.0, v189
	v_add_f32_e32 v190, 1.0, v190
	v_add_f32_e32 v191, 1.0, v191
	v_add_f32_e32 v192, 1.0, v192
	v_rcp_f32_e32 v166, v189
	v_rcp_f32_e32 v167, v190
	s_nop 0
	v_fma_f32 v189, -v189, v166, 2.0
	v_fma_f32 v190, -v190, v167, 2.0
	v_mul_f32_e32 v166, v166, v189
	v_mul_f32_e32 v167, v167, v190
	v_mul_f32_e32 v182, v182, v166
	v_mul_f32_e32 v183, v183, v167
	v_rcp_f32_e32 v166, v191
	v_rcp_f32_e32 v167, v192
	s_nop 0
	v_fma_f32 v191, -v191, v166, 2.0
	v_fma_f32 v192, -v192, v167, 2.0
	v_mul_f32_e32 v166, v166, v191
	v_mul_f32_e32 v167, v167, v192
	v_mul_f32_e32 v184, v184, v166
	v_mul_f32_e32 v185, v185, v167
	v_mul_f32_e32 v112, v182, v112
	v_mul_f32_e32 v113, v183, v113
	v_mul_f32_e32 v114, v184, v114
	v_mul_f32_e32 v115, v185, v115
	v_cvt_pk_bf16_f32 v112, v112, v113
	v_cvt_pk_bf16_f32 v113, v114, v115
	ds_write_b64 v160, v[112:113]
	ds_read_b64 v[164:165], v160 offset:16
	s_waitcnt vmcnt(2) lgkmcnt(0)
	v_lshlrev_b32_e32 v182, 16, v164
	v_and_b32_e32 v183, 0xffff0000, v164
	v_lshlrev_b32_e32 v184, 16, v165
	v_and_b32_e32 v185, 0xffff0000, v165
	v_add_f32_e32 v116, v132, v116
	v_mul_f32_e32 v116, v148, v116
	v_add_f32_e32 v117, v133, v117
	v_mul_f32_e32 v117, v149, v117
	v_add_f32_e32 v118, v134, v118
	v_mul_f32_e32 v118, v150, v118
	v_add_f32_e32 v119, v135, v119
	v_mul_f32_e32 v119, v151, v119
	v_mul_f32_e32 v189, 0xbfb8aa3b, v182
	v_mul_f32_e32 v190, 0xbfb8aa3b, v183
	v_mul_f32_e32 v191, 0xbfb8aa3b, v184
	v_mul_f32_e32 v192, 0xbfb8aa3b, v185
	v_exp_f32_e32 v189, v189
	v_exp_f32_e32 v190, v190
	v_exp_f32_e32 v191, v191
	v_exp_f32_e32 v192, v192
	s_nop 0
	v_add_f32_e32 v189, 1.0, v189
	v_add_f32_e32 v190, 1.0, v190
	v_add_f32_e32 v191, 1.0, v191
	v_add_f32_e32 v192, 1.0, v192
	v_rcp_f32_e32 v166, v189
	v_rcp_f32_e32 v167, v190
	s_nop 0
	v_fma_f32 v189, -v189, v166, 2.0
	v_fma_f32 v190, -v190, v167, 2.0
	v_mul_f32_e32 v166, v166, v189
	v_mul_f32_e32 v167, v167, v190
	v_mul_f32_e32 v182, v182, v166
	v_mul_f32_e32 v183, v183, v167
	v_rcp_f32_e32 v166, v191
	v_rcp_f32_e32 v167, v192
	s_nop 0
	v_fma_f32 v191, -v191, v166, 2.0
	v_fma_f32 v192, -v192, v167, 2.0
	v_mul_f32_e32 v166, v166, v191
	v_mul_f32_e32 v167, v167, v192
	v_mul_f32_e32 v184, v184, v166
	v_mul_f32_e32 v185, v185, v167
	v_mul_f32_e32 v116, v182, v116
	v_mul_f32_e32 v117, v183, v117
	v_mul_f32_e32 v118, v184, v118
	v_mul_f32_e32 v119, v185, v119
	v_cvt_pk_bf16_f32 v116, v116, v117
	v_cvt_pk_bf16_f32 v117, v118, v119
	ds_write_b64 v160, v[116:117] offset:16
	ds_read_b64 v[164:165], v160 offset:32
	s_waitcnt vmcnt(1) lgkmcnt(0)
	v_lshlrev_b32_e32 v182, 16, v164
	v_and_b32_e32 v183, 0xffff0000, v164
	v_lshlrev_b32_e32 v184, 16, v165
	v_and_b32_e32 v185, 0xffff0000, v165
	v_add_f32_e32 v120, v136, v120
	v_mul_f32_e32 v120, v152, v120
	v_add_f32_e32 v121, v137, v121
	v_mul_f32_e32 v121, v153, v121
	v_add_f32_e32 v122, v138, v122
	v_mul_f32_e32 v122, v154, v122
	v_add_f32_e32 v123, v139, v123
	v_mul_f32_e32 v123, v155, v123
	v_mul_f32_e32 v189, 0xbfb8aa3b, v182
	v_mul_f32_e32 v190, 0xbfb8aa3b, v183
	v_mul_f32_e32 v191, 0xbfb8aa3b, v184
	v_mul_f32_e32 v192, 0xbfb8aa3b, v185
	v_exp_f32_e32 v189, v189
	v_exp_f32_e32 v190, v190
	v_exp_f32_e32 v191, v191
	v_exp_f32_e32 v192, v192
	s_nop 0
	v_add_f32_e32 v189, 1.0, v189
	v_add_f32_e32 v190, 1.0, v190
	v_add_f32_e32 v191, 1.0, v191
	v_add_f32_e32 v192, 1.0, v192
	v_rcp_f32_e32 v166, v189
	v_rcp_f32_e32 v167, v190
	s_nop 0
	v_fma_f32 v189, -v189, v166, 2.0
	v_fma_f32 v190, -v190, v167, 2.0
	v_mul_f32_e32 v166, v166, v189
	v_mul_f32_e32 v167, v167, v190
	v_mul_f32_e32 v182, v182, v166
	v_mul_f32_e32 v183, v183, v167
	v_rcp_f32_e32 v166, v191
	v_rcp_f32_e32 v167, v192
	s_nop 0
	v_fma_f32 v191, -v191, v166, 2.0
	v_fma_f32 v192, -v192, v167, 2.0
	v_mul_f32_e32 v166, v166, v191
	v_mul_f32_e32 v167, v167, v192
	v_mul_f32_e32 v184, v184, v166
	v_mul_f32_e32 v185, v185, v167
	v_mul_f32_e32 v120, v182, v120
	v_mul_f32_e32 v121, v183, v121
	v_mul_f32_e32 v122, v184, v122
	v_mul_f32_e32 v123, v185, v123
	v_cvt_pk_bf16_f32 v120, v120, v121
	v_cvt_pk_bf16_f32 v121, v122, v123
	ds_write_b64 v160, v[120:121] offset:32
	ds_read_b64 v[164:165], v160 offset:48
	s_waitcnt vmcnt(0) lgkmcnt(0)
; DI bfr f2bf(float a) { return (bfr)(pack2(a, 0.f) & 0xffffu); }
; DI float bf2f(bfr u) { return __uint_as_float(((unsigned)u) << 16); }
; DI float siluf_(float x) { return x / (1.0f + __expf(-x)); }
; DI void phase_gemm_pool(const Params& p, char* smem) {
;     ...
;                 float gate = bf2f(P2[(size_t)row * 2048 + 1024 + g * 256 + col]);
;                 float z = (v + bp[col]) * sc[col] * siluf_(gate);
;                 Z[(size_t)row * 1024 + g * 256 + col] = f2bf(z);
	v_lshlrev_b32_e32 v182, 16, v164
	v_and_b32_e32 v183, 0xffff0000, v164
	v_lshlrev_b32_e32 v184, 16, v165
	v_and_b32_e32 v185, 0xffff0000, v165
	v_add_f32_e32 v124, v140, v124
	v_mul_f32_e32 v124, v156, v124
	v_add_f32_e32 v125, v141, v125
	v_mul_f32_e32 v125, v157, v125
	v_add_f32_e32 v126, v142, v126
	v_mul_f32_e32 v126, v158, v126
	v_add_f32_e32 v127, v143, v127
	v_mul_f32_e32 v127, v159, v127
	v_mul_f32_e32 v189, 0xbfb8aa3b, v182
	v_mul_f32_e32 v190, 0xbfb8aa3b, v183
	v_mul_f32_e32 v191, 0xbfb8aa3b, v184
	v_mul_f32_e32 v192, 0xbfb8aa3b, v185
	v_exp_f32_e32 v189, v189
	v_exp_f32_e32 v190, v190
	v_exp_f32_e32 v191, v191
	v_exp_f32_e32 v192, v192
	s_nop 0
	v_add_f32_e32 v189, 1.0, v189
	v_add_f32_e32 v190, 1.0, v190
	v_add_f32_e32 v191, 1.0, v191
	v_add_f32_e32 v192, 1.0, v192
	v_rcp_f32_e32 v166, v189
	v_rcp_f32_e32 v167, v190
	s_nop 0
	v_fma_f32 v189, -v189, v166, 2.0
	v_fma_f32 v190, -v190, v167, 2.0
	v_mul_f32_e32 v166, v166, v189
	v_mul_f32_e32 v167, v167, v190
	v_mul_f32_e32 v182, v182, v166
	v_mul_f32_e32 v183, v183, v167
	v_rcp_f32_e32 v166, v191
	v_rcp_f32_e32 v167, v192
	s_nop 0
	v_fma_f32 v191, -v191, v166, 2.0
	v_fma_f32 v192, -v192, v167, 2.0
	v_mul_f32_e32 v166, v166, v191
	v_mul_f32_e32 v167, v167, v192
	v_mul_f32_e32 v184, v184, v166
	v_mul_f32_e32 v185, v185, v167
	v_mul_f32_e32 v124, v182, v124
	v_mul_f32_e32 v125, v183, v125
	v_mul_f32_e32 v126, v184, v126
	v_mul_f32_e32 v127, v185, v127
	v_cvt_pk_bf16_f32 v124, v124, v125
	v_cvt_pk_bf16_f32 v125, v126, v127
	ds_write_b64 v160, v[124:125] offset:48
	global_load_dwordx4 v[128:131], v181, s[68:69] offset:128
	global_load_dwordx4 v[132:135], v181, s[68:69] offset:160
	global_load_dwordx4 v[136:139], v181, s[68:69] offset:192
	global_load_dwordx4 v[140:143], v181, s[68:69] offset:224
	global_load_dwordx4 v[144:147], v181, s[70:71] offset:128
	global_load_dwordx4 v[148:151], v181, s[70:71] offset:160
	global_load_dwordx4 v[152:155], v181, s[70:71] offset:192
	global_load_dwordx4 v[156:159], v181, s[70:71] offset:224
	ds_read_b64 v[164:165], v160 offset:64
	s_waitcnt vmcnt(3) lgkmcnt(0)
	v_lshlrev_b32_e32 v182, 16, v164
	v_and_b32_e32 v183, 0xffff0000, v164
	v_lshlrev_b32_e32 v184, 16, v165
	v_and_b32_e32 v185, 0xffff0000, v165
	v_add_f32_e32 v96, v128, v96
	v_mul_f32_e32 v96, v144, v96
	v_add_f32_e32 v97, v129, v97
	v_mul_f32_e32 v97, v145, v97
	v_add_f32_e32 v98, v130, v98
	v_mul_f32_e32 v98, v146, v98
	v_add_f32_e32 v99, v131, v99
	v_mul_f32_e32 v99, v147, v99
	v_mul_f32_e32 v189, 0xbfb8aa3b, v182
	v_mul_f32_e32 v190, 0xbfb8aa3b, v183
	v_mul_f32_e32 v191, 0xbfb8aa3b, v184
	v_mul_f32_e32 v192, 0xbfb8aa3b, v185
	v_exp_f32_e32 v189, v189
	v_exp_f32_e32 v190, v190
	v_exp_f32_e32 v191, v191
	v_exp_f32_e32 v192, v192
	s_nop 0
	v_add_f32_e32 v189, 1.0, v189
	v_add_f32_e32 v190, 1.0, v190
	v_add_f32_e32 v191, 1.0, v191
	v_add_f32_e32 v192, 1.0, v192
	v_rcp_f32_e32 v166, v189
	v_rcp_f32_e32 v167, v190
	s_nop 0
	v_fma_f32 v189, -v189, v166, 2.0
	v_fma_f32 v190, -v190, v167, 2.0
	v_mul_f32_e32 v166, v166, v189
	v_mul_f32_e32 v167, v167, v190
	v_mul_f32_e32 v182, v182, v166
	v_mul_f32_e32 v183, v183, v167
	v_rcp_f32_e32 v166, v191
	v_rcp_f32_e32 v167, v192
	s_nop 0
	v_fma_f32 v191, -v191, v166, 2.0
	v_fma_f32 v192, -v192, v167, 2.0
	v_mul_f32_e32 v166, v166, v191
	v_mul_f32_e32 v167, v167, v192
	v_mul_f32_e32 v184, v184, v166
	v_mul_f32_e32 v185, v185, v167
	v_mul_f32_e32 v96, v182, v96
	v_mul_f32_e32 v97, v183, v97
	v_mul_f32_e32 v98, v184, v98
	v_mul_f32_e32 v99, v185, v99
	v_cvt_pk_bf16_f32 v96, v96, v97
	v_cvt_pk_bf16_f32 v97, v98, v99
	ds_write_b64 v160, v[96:97] offset:64
	ds_read_b64 v[164:165], v160 offset:80
	s_waitcnt vmcnt(2) lgkmcnt(0)
	v_lshlrev_b32_e32 v182, 16, v164
	v_and_b32_e32 v183, 0xffff0000, v164
	v_lshlrev_b32_e32 v184, 16, v165
	v_and_b32_e32 v185, 0xffff0000, v165
	v_add_f32_e32 v100, v132, v100
	v_mul_f32_e32 v100, v148, v100
	v_add_f32_e32 v101, v133, v101
	v_mul_f32_e32 v101, v149, v101
	v_add_f32_e32 v102, v134, v102
	v_mul_f32_e32 v102, v150, v102
	v_add_f32_e32 v103, v135, v103
	v_mul_f32_e32 v103, v151, v103
	v_mul_f32_e32 v189, 0xbfb8aa3b, v182
	v_mul_f32_e32 v190, 0xbfb8aa3b, v183
	v_mul_f32_e32 v191, 0xbfb8aa3b, v184
	v_mul_f32_e32 v192, 0xbfb8aa3b, v185
	v_exp_f32_e32 v189, v189
	v_exp_f32_e32 v190, v190
	v_exp_f32_e32 v191, v191
	v_exp_f32_e32 v192, v192
	s_nop 0
	v_add_f32_e32 v189, 1.0, v189
	v_add_f32_e32 v190, 1.0, v190
	v_add_f32_e32 v191, 1.0, v191
	v_add_f32_e32 v192, 1.0, v192
	v_rcp_f32_e32 v166, v189
	v_rcp_f32_e32 v167, v190
	s_nop 0
	v_fma_f32 v189, -v189, v166, 2.0
	v_fma_f32 v190, -v190, v167, 2.0
	v_mul_f32_e32 v166, v166, v189
	v_mul_f32_e32 v167, v167, v190
	v_mul_f32_e32 v182, v182, v166
	v_mul_f32_e32 v183, v183, v167
	v_rcp_f32_e32 v166, v191
	v_rcp_f32_e32 v167, v192
	s_nop 0
	v_fma_f32 v191, -v191, v166, 2.0
	v_fma_f32 v192, -v192, v167, 2.0
	v_mul_f32_e32 v166, v166, v191
	v_mul_f32_e32 v167, v167, v192
	v_mul_f32_e32 v184, v184, v166
	v_mul_f32_e32 v185, v185, v167
	v_mul_f32_e32 v100, v182, v100
	v_mul_f32_e32 v101, v183, v101
	v_mul_f32_e32 v102, v184, v102
	v_mul_f32_e32 v103, v185, v103
	v_cvt_pk_bf16_f32 v100, v100, v101
	v_cvt_pk_bf16_f32 v101, v102, v103
	ds_write_b64 v160, v[100:101] offset:80
	ds_read_b64 v[164:165], v160 offset:96
	s_waitcnt vmcnt(1) lgkmcnt(0)
; DI bfr f2bf(float a) { return (bfr)(pack2(a, 0.f) & 0xffffu); }
; DI float bf2f(bfr u) { return __uint_as_float(((unsigned)u) << 16); }
; DI float siluf_(float x) { return x / (1.0f + __expf(-x)); }
; DI void phase_gemm_pool(const Params& p, char* smem) {
;     ...
;                 float gate = bf2f(P2[(size_t)row * 2048 + 1024 + g * 256 + col]);
;                 float z = (v + bp[col]) * sc[col] * siluf_(gate);
;                 Z[(size_t)row * 1024 + g * 256 + col] = f2bf(z);
	v_lshlrev_b32_e32 v182, 16, v164
	v_and_b32_e32 v183, 0xffff0000, v164
	v_lshlrev_b32_e32 v184, 16, v165
	v_and_b32_e32 v185, 0xffff0000, v165
	v_add_f32_e32 v104, v136, v104
	v_mul_f32_e32 v104, v152, v104
	v_add_f32_e32 v105, v137, v105
	v_mul_f32_e32 v105, v153, v105
	v_add_f32_e32 v106, v138, v106
	v_mul_f32_e32 v106, v154, v106
	v_add_f32_e32 v107, v139, v107
	v_mul_f32_e32 v107, v155, v107
	v_mul_f32_e32 v189, 0xbfb8aa3b, v182
	v_mul_f32_e32 v190, 0xbfb8aa3b, v183
	v_mul_f32_e32 v191, 0xbfb8aa3b, v184
	v_mul_f32_e32 v192, 0xbfb8aa3b, v185
	v_exp_f32_e32 v189, v189
	v_exp_f32_e32 v190, v190
	v_exp_f32_e32 v191, v191
	v_exp_f32_e32 v192, v192
	s_nop 0
	v_add_f32_e32 v189, 1.0, v189
	v_add_f32_e32 v190, 1.0, v190
	v_add_f32_e32 v191, 1.0, v191
	v_add_f32_e32 v192, 1.0, v192
	v_rcp_f32_e32 v166, v189
	v_rcp_f32_e32 v167, v190
	s_nop 0
	v_fma_f32 v189, -v189, v166, 2.0
	v_fma_f32 v190, -v190, v167, 2.0
	v_mul_f32_e32 v166, v166, v189
	v_mul_f32_e32 v167, v167, v190
	v_mul_f32_e32 v182, v182, v166
	v_mul_f32_e32 v183, v183, v167
	v_rcp_f32_e32 v166, v191
	v_rcp_f32_e32 v167, v192
	s_nop 0
	v_fma_f32 v191, -v191, v166, 2.0
	v_fma_f32 v192, -v192, v167, 2.0
	v_mul_f32_e32 v166, v166, v191
	v_mul_f32_e32 v167, v167, v192
	v_mul_f32_e32 v184, v184, v166
	v_mul_f32_e32 v185, v185, v167
	v_mul_f32_e32 v104, v182, v104
	v_mul_f32_e32 v105, v183, v105
	v_mul_f32_e32 v106, v184, v106
	v_mul_f32_e32 v107, v185, v107
	v_cvt_pk_bf16_f32 v104, v104, v105
	v_cvt_pk_bf16_f32 v105, v106, v107
	ds_write_b64 v160, v[104:105] offset:96
	ds_read_b64 v[164:165], v160 offset:112
	s_waitcnt vmcnt(0) lgkmcnt(0)
	v_lshlrev_b32_e32 v182, 16, v164
	v_and_b32_e32 v183, 0xffff0000, v164
	v_lshlrev_b32_e32 v184, 16, v165
	v_and_b32_e32 v185, 0xffff0000, v165
	v_add_f32_e32 v108, v140, v108
	v_mul_f32_e32 v108, v156, v108
	v_add_f32_e32 v109, v141, v109
	v_mul_f32_e32 v109, v157, v109
	v_add_f32_e32 v110, v142, v110
	v_mul_f32_e32 v110, v158, v110
	v_add_f32_e32 v111, v143, v111
	v_mul_f32_e32 v111, v159, v111
	v_mul_f32_e32 v189, 0xbfb8aa3b, v182
	v_mul_f32_e32 v190, 0xbfb8aa3b, v183
	v_mul_f32_e32 v191, 0xbfb8aa3b, v184
	v_mul_f32_e32 v192, 0xbfb8aa3b, v185
	v_exp_f32_e32 v189, v189
	v_exp_f32_e32 v190, v190
	v_exp_f32_e32 v191, v191
	v_exp_f32_e32 v192, v192
	s_nop 0
	v_add_f32_e32 v189, 1.0, v189
	v_add_f32_e32 v190, 1.0, v190
	v_add_f32_e32 v191, 1.0, v191
	v_add_f32_e32 v192, 1.0, v192
	v_rcp_f32_e32 v166, v189
	v_rcp_f32_e32 v167, v190
	s_nop 0
	v_fma_f32 v189, -v189, v166, 2.0
	v_fma_f32 v190, -v190, v167, 2.0
	v_mul_f32_e32 v166, v166, v189
	v_mul_f32_e32 v167, v167, v190
	v_mul_f32_e32 v182, v182, v166
	v_mul_f32_e32 v183, v183, v167
	v_rcp_f32_e32 v166, v191
	v_rcp_f32_e32 v167, v192
	s_nop 0
	v_fma_f32 v191, -v191, v166, 2.0
	v_fma_f32 v192, -v192, v167, 2.0
	v_mul_f32_e32 v166, v166, v191
	v_mul_f32_e32 v167, v167, v192
	v_mul_f32_e32 v184, v184, v166
	v_mul_f32_e32 v185, v185, v167
	v_mul_f32_e32 v108, v182, v108
	v_mul_f32_e32 v109, v183, v109
	v_mul_f32_e32 v110, v184, v110
	v_mul_f32_e32 v111, v185, v111
	v_cvt_pk_bf16_f32 v108, v108, v109
	v_cvt_pk_bf16_f32 v109, v110, v111
	ds_write_b64 v160, v[108:109] offset:112
	global_load_dwordx4 v[128:131], v181, s[68:69] offset:256
	global_load_dwordx4 v[132:135], v181, s[68:69] offset:288
	global_load_dwordx4 v[136:139], v181, s[68:69] offset:320
	global_load_dwordx4 v[140:143], v181, s[68:69] offset:352
	global_load_dwordx4 v[144:147], v181, s[70:71] offset:256
	global_load_dwordx4 v[148:151], v181, s[70:71] offset:288
	global_load_dwordx4 v[152:155], v181, s[70:71] offset:320
	global_load_dwordx4 v[156:159], v181, s[70:71] offset:352
	ds_read_b64 v[164:165], v160 offset:128
	s_waitcnt vmcnt(3) lgkmcnt(0)
	v_lshlrev_b32_e32 v182, 16, v164
	v_and_b32_e32 v183, 0xffff0000, v164
	v_lshlrev_b32_e32 v184, 16, v165
	v_and_b32_e32 v185, 0xffff0000, v165
	v_add_f32_e32 v80, v128, v80
	v_mul_f32_e32 v80, v144, v80
	v_add_f32_e32 v81, v129, v81
	v_mul_f32_e32 v81, v145, v81
	v_add_f32_e32 v82, v130, v82
	v_mul_f32_e32 v82, v146, v82
	v_add_f32_e32 v83, v131, v83
	v_mul_f32_e32 v83, v147, v83
	v_mul_f32_e32 v189, 0xbfb8aa3b, v182
	v_mul_f32_e32 v190, 0xbfb8aa3b, v183
	v_mul_f32_e32 v191, 0xbfb8aa3b, v184
	v_mul_f32_e32 v192, 0xbfb8aa3b, v185
	v_exp_f32_e32 v189, v189
	v_exp_f32_e32 v190, v190
	v_exp_f32_e32 v191, v191
	v_exp_f32_e32 v192, v192
	s_nop 0
	v_add_f32_e32 v189, 1.0, v189
	v_add_f32_e32 v190, 1.0, v190
	v_add_f32_e32 v191, 1.0, v191
	v_add_f32_e32 v192, 1.0, v192
	v_rcp_f32_e32 v166, v189
	v_rcp_f32_e32 v167, v190
	s_nop 0
	v_fma_f32 v189, -v189, v166, 2.0
	v_fma_f32 v190, -v190, v167, 2.0
	v_mul_f32_e32 v166, v166, v189
	v_mul_f32_e32 v167, v167, v190
	v_mul_f32_e32 v182, v182, v166
	v_mul_f32_e32 v183, v183, v167
	v_rcp_f32_e32 v166, v191
	v_rcp_f32_e32 v167, v192
	s_nop 0
	v_fma_f32 v191, -v191, v166, 2.0
	v_fma_f32 v192, -v192, v167, 2.0
	v_mul_f32_e32 v166, v166, v191
	v_mul_f32_e32 v167, v167, v192
	v_mul_f32_e32 v184, v184, v166
	v_mul_f32_e32 v185, v185, v167
	v_mul_f32_e32 v80, v182, v80
	v_mul_f32_e32 v81, v183, v81
	v_mul_f32_e32 v82, v184, v82
	v_mul_f32_e32 v83, v185, v83
	v_cvt_pk_bf16_f32 v80, v80, v81
	v_cvt_pk_bf16_f32 v81, v82, v83
	ds_write_b64 v160, v[80:81] offset:128
	ds_read_b64 v[164:165], v160 offset:144
	s_waitcnt vmcnt(2) lgkmcnt(0)
; DI bfr f2bf(float a) { return (bfr)(pack2(a, 0.f) & 0xffffu); }
; DI float bf2f(bfr u) { return __uint_as_float(((unsigned)u) << 16); }
; DI float siluf_(float x) { return x / (1.0f + __expf(-x)); }
; DI void phase_gemm_pool(const Params& p, char* smem) {
;     ...
;                 float gate = bf2f(P2[(size_t)row * 2048 + 1024 + g * 256 + col]);
;                 float z = (v + bp[col]) * sc[col] * siluf_(gate);
;                 Z[(size_t)row * 1024 + g * 256 + col] = f2bf(z);
	v_lshlrev_b32_e32 v182, 16, v164
	v_and_b32_e32 v183, 0xffff0000, v164
	v_lshlrev_b32_e32 v184, 16, v165
	v_and_b32_e32 v185, 0xffff0000, v165
	v_add_f32_e32 v84, v132, v84
	v_mul_f32_e32 v84, v148, v84
	v_add_f32_e32 v85, v133, v85
	v_mul_f32_e32 v85, v149, v85
	v_add_f32_e32 v86, v134, v86
	v_mul_f32_e32 v86, v150, v86
	v_add_f32_e32 v87, v135, v87
	v_mul_f32_e32 v87, v151, v87
	v_mul_f32_e32 v189, 0xbfb8aa3b, v182
	v_mul_f32_e32 v190, 0xbfb8aa3b, v183
	v_mul_f32_e32 v191, 0xbfb8aa3b, v184
	v_mul_f32_e32 v192, 0xbfb8aa3b, v185
	v_exp_f32_e32 v189, v189
	v_exp_f32_e32 v190, v190
	v_exp_f32_e32 v191, v191
	v_exp_f32_e32 v192, v192
	s_nop 0
	v_add_f32_e32 v189, 1.0, v189
	v_add_f32_e32 v190, 1.0, v190
	v_add_f32_e32 v191, 1.0, v191
	v_add_f32_e32 v192, 1.0, v192
	v_rcp_f32_e32 v166, v189
	v_rcp_f32_e32 v167, v190
	s_nop 0
	v_fma_f32 v189, -v189, v166, 2.0
	v_fma_f32 v190, -v190, v167, 2.0
	v_mul_f32_e32 v166, v166, v189
	v_mul_f32_e32 v167, v167, v190
	v_mul_f32_e32 v182, v182, v166
	v_mul_f32_e32 v183, v183, v167
	v_rcp_f32_e32 v166, v191
	v_rcp_f32_e32 v167, v192
	s_nop 0
	v_fma_f32 v191, -v191, v166, 2.0
	v_fma_f32 v192, -v192, v167, 2.0
	v_mul_f32_e32 v166, v166, v191
	v_mul_f32_e32 v167, v167, v192
	v_mul_f32_e32 v184, v184, v166
	v_mul_f32_e32 v185, v185, v167
	v_mul_f32_e32 v84, v182, v84
	v_mul_f32_e32 v85, v183, v85
	v_mul_f32_e32 v86, v184, v86
	v_mul_f32_e32 v87, v185, v87
	v_cvt_pk_bf16_f32 v84, v84, v85
	v_cvt_pk_bf16_f32 v85, v86, v87
	ds_write_b64 v160, v[84:85] offset:144
	ds_read_b64 v[164:165], v160 offset:160
	s_waitcnt vmcnt(1) lgkmcnt(0)
	v_lshlrev_b32_e32 v182, 16, v164
	v_and_b32_e32 v183, 0xffff0000, v164
	v_lshlrev_b32_e32 v184, 16, v165
	v_and_b32_e32 v185, 0xffff0000, v165
	v_add_f32_e32 v88, v136, v88
	v_mul_f32_e32 v88, v152, v88
	v_add_f32_e32 v89, v137, v89
	v_mul_f32_e32 v89, v153, v89
	v_add_f32_e32 v90, v138, v90
	v_mul_f32_e32 v90, v154, v90
	v_add_f32_e32 v91, v139, v91
	v_mul_f32_e32 v91, v155, v91
	v_mul_f32_e32 v189, 0xbfb8aa3b, v182
	v_mul_f32_e32 v190, 0xbfb8aa3b, v183
	v_mul_f32_e32 v191, 0xbfb8aa3b, v184
	v_mul_f32_e32 v192, 0xbfb8aa3b, v185
	v_exp_f32_e32 v189, v189
	v_exp_f32_e32 v190, v190
	v_exp_f32_e32 v191, v191
	v_exp_f32_e32 v192, v192
	s_nop 0
	v_add_f32_e32 v189, 1.0, v189
	v_add_f32_e32 v190, 1.0, v190
	v_add_f32_e32 v191, 1.0, v191
	v_add_f32_e32 v192, 1.0, v192
	v_rcp_f32_e32 v166, v189
	v_rcp_f32_e32 v167, v190
	s_nop 0
	v_fma_f32 v189, -v189, v166, 2.0
	v_fma_f32 v190, -v190, v167, 2.0
	v_mul_f32_e32 v166, v166, v189
	v_mul_f32_e32 v167, v167, v190
	v_mul_f32_e32 v182, v182, v166
	v_mul_f32_e32 v183, v183, v167
	v_rcp_f32_e32 v166, v191
	v_rcp_f32_e32 v167, v192
	s_nop 0
	v_fma_f32 v191, -v191, v166, 2.0
	v_fma_f32 v192, -v192, v167, 2.0
	v_mul_f32_e32 v166, v166, v191
	v_mul_f32_e32 v167, v167, v192
	v_mul_f32_e32 v184, v184, v166
	v_mul_f32_e32 v185, v185, v167
	v_mul_f32_e32 v88, v182, v88
	v_mul_f32_e32 v89, v183, v89
	v_mul_f32_e32 v90, v184, v90
	v_mul_f32_e32 v91, v185, v91
	v_cvt_pk_bf16_f32 v88, v88, v89
	v_cvt_pk_bf16_f32 v89, v90, v91
	ds_write_b64 v160, v[88:89] offset:160
	ds_read_b64 v[164:165], v160 offset:176
	s_waitcnt vmcnt(0) lgkmcnt(0)
	v_lshlrev_b32_e32 v182, 16, v164
	v_and_b32_e32 v183, 0xffff0000, v164
	v_lshlrev_b32_e32 v184, 16, v165
	v_and_b32_e32 v185, 0xffff0000, v165
	v_add_f32_e32 v92, v140, v92
	v_mul_f32_e32 v92, v156, v92
	v_add_f32_e32 v93, v141, v93
	v_mul_f32_e32 v93, v157, v93
	v_add_f32_e32 v94, v142, v94
	v_mul_f32_e32 v94, v158, v94
	v_add_f32_e32 v95, v143, v95
	v_mul_f32_e32 v95, v159, v95
	v_mul_f32_e32 v189, 0xbfb8aa3b, v182
	v_mul_f32_e32 v190, 0xbfb8aa3b, v183
	v_mul_f32_e32 v191, 0xbfb8aa3b, v184
	v_mul_f32_e32 v192, 0xbfb8aa3b, v185
	v_exp_f32_e32 v189, v189
	v_exp_f32_e32 v190, v190
	v_exp_f32_e32 v191, v191
	v_exp_f32_e32 v192, v192
	s_nop 0
	v_add_f32_e32 v189, 1.0, v189
	v_add_f32_e32 v190, 1.0, v190
	v_add_f32_e32 v191, 1.0, v191
	v_add_f32_e32 v192, 1.0, v192
	v_rcp_f32_e32 v166, v189
	v_rcp_f32_e32 v167, v190
	s_nop 0
	v_fma_f32 v189, -v189, v166, 2.0
	v_fma_f32 v190, -v190, v167, 2.0
	v_mul_f32_e32 v166, v166, v189
	v_mul_f32_e32 v167, v167, v190
	v_mul_f32_e32 v182, v182, v166
	v_mul_f32_e32 v183, v183, v167
	v_rcp_f32_e32 v166, v191
	v_rcp_f32_e32 v167, v192
	s_nop 0
	v_fma_f32 v191, -v191, v166, 2.0
	v_fma_f32 v192, -v192, v167, 2.0
	v_mul_f32_e32 v166, v166, v191
	v_mul_f32_e32 v167, v167, v192
	v_mul_f32_e32 v184, v184, v166
	v_mul_f32_e32 v185, v185, v167
	v_mul_f32_e32 v92, v182, v92
	v_mul_f32_e32 v93, v183, v93
	v_mul_f32_e32 v94, v184, v94
	v_mul_f32_e32 v95, v185, v95
	v_cvt_pk_bf16_f32 v92, v92, v93
	v_cvt_pk_bf16_f32 v93, v94, v95
	ds_write_b64 v160, v[92:93] offset:176
	global_load_dwordx4 v[128:131], v181, s[68:69] offset:384
	global_load_dwordx4 v[132:135], v181, s[68:69] offset:416
	global_load_dwordx4 v[136:139], v181, s[68:69] offset:448
	global_load_dwordx4 v[140:143], v181, s[68:69] offset:480
	global_load_dwordx4 v[144:147], v181, s[70:71] offset:384
	global_load_dwordx4 v[148:151], v181, s[70:71] offset:416
	global_load_dwordx4 v[152:155], v181, s[70:71] offset:448
	global_load_dwordx4 v[156:159], v181, s[70:71] offset:480
	ds_read_b64 v[164:165], v160 offset:192
	s_waitcnt vmcnt(3) lgkmcnt(0)
; DI bfr f2bf(float a) { return (bfr)(pack2(a, 0.f) & 0xffffu); }
; DI float bf2f(bfr u) { return __uint_as_float(((unsigned)u) << 16); }
; DI float siluf_(float x) { return x / (1.0f + __expf(-x)); }
; DI void phase_gemm_pool(const Params& p, char* smem) {
;     ...
;                 float gate = bf2f(P2[(size_t)row * 2048 + 1024 + g * 256 + col]);
;                 float z = (v + bp[col]) * sc[col] * siluf_(gate);
;                 Z[(size_t)row * 1024 + g * 256 + col] = f2bf(z);
	v_lshlrev_b32_e32 v182, 16, v164
	v_and_b32_e32 v183, 0xffff0000, v164
	v_lshlrev_b32_e32 v184, 16, v165
	v_and_b32_e32 v185, 0xffff0000, v165
	v_add_f32_e32 v64, v128, v64
	v_mul_f32_e32 v64, v144, v64
	v_add_f32_e32 v65, v129, v65
	v_mul_f32_e32 v65, v145, v65
	v_add_f32_e32 v66, v130, v66
	v_mul_f32_e32 v66, v146, v66
	v_add_f32_e32 v67, v131, v67
	v_mul_f32_e32 v67, v147, v67
	v_mul_f32_e32 v189, 0xbfb8aa3b, v182
	v_mul_f32_e32 v190, 0xbfb8aa3b, v183
	v_mul_f32_e32 v191, 0xbfb8aa3b, v184
	v_mul_f32_e32 v192, 0xbfb8aa3b, v185
	v_exp_f32_e32 v189, v189
	v_exp_f32_e32 v190, v190
	v_exp_f32_e32 v191, v191
	v_exp_f32_e32 v192, v192
	s_nop 0
	v_add_f32_e32 v189, 1.0, v189
	v_add_f32_e32 v190, 1.0, v190
	v_add_f32_e32 v191, 1.0, v191
	v_add_f32_e32 v192, 1.0, v192
	v_rcp_f32_e32 v166, v189
	v_rcp_f32_e32 v167, v190
	s_nop 0
	v_fma_f32 v189, -v189, v166, 2.0
	v_fma_f32 v190, -v190, v167, 2.0
	v_mul_f32_e32 v166, v166, v189
	v_mul_f32_e32 v167, v167, v190
	v_mul_f32_e32 v182, v182, v166
	v_mul_f32_e32 v183, v183, v167
	v_rcp_f32_e32 v166, v191
	v_rcp_f32_e32 v167, v192
	s_nop 0
	v_fma_f32 v191, -v191, v166, 2.0
	v_fma_f32 v192, -v192, v167, 2.0
	v_mul_f32_e32 v166, v166, v191
	v_mul_f32_e32 v167, v167, v192
	v_mul_f32_e32 v184, v184, v166
	v_mul_f32_e32 v185, v185, v167
	v_mul_f32_e32 v64, v182, v64
	v_mul_f32_e32 v65, v183, v65
	v_mul_f32_e32 v66, v184, v66
	v_mul_f32_e32 v67, v185, v67
	v_cvt_pk_bf16_f32 v64, v64, v65
	v_cvt_pk_bf16_f32 v65, v66, v67
	ds_write_b64 v160, v[64:65] offset:192
	ds_read_b64 v[164:165], v160 offset:208
	s_waitcnt vmcnt(2) lgkmcnt(0)
	v_lshlrev_b32_e32 v182, 16, v164
	v_and_b32_e32 v183, 0xffff0000, v164
	v_lshlrev_b32_e32 v184, 16, v165
	v_and_b32_e32 v185, 0xffff0000, v165
	v_add_f32_e32 v68, v132, v68
	v_mul_f32_e32 v68, v148, v68
	v_add_f32_e32 v69, v133, v69
	v_mul_f32_e32 v69, v149, v69
	v_add_f32_e32 v70, v134, v70
	v_mul_f32_e32 v70, v150, v70
	v_add_f32_e32 v71, v135, v71
	v_mul_f32_e32 v71, v151, v71
	v_mul_f32_e32 v189, 0xbfb8aa3b, v182
	v_mul_f32_e32 v190, 0xbfb8aa3b, v183
	v_mul_f32_e32 v191, 0xbfb8aa3b, v184
	v_mul_f32_e32 v192, 0xbfb8aa3b, v185
	v_exp_f32_e32 v189, v189
	v_exp_f32_e32 v190, v190
	v_exp_f32_e32 v191, v191
	v_exp_f32_e32 v192, v192
	s_nop 0
	v_add_f32_e32 v189, 1.0, v189
	v_add_f32_e32 v190, 1.0, v190
	v_add_f32_e32 v191, 1.0, v191
	v_add_f32_e32 v192, 1.0, v192
	v_rcp_f32_e32 v166, v189
	v_rcp_f32_e32 v167, v190
	s_nop 0
	v_fma_f32 v189, -v189, v166, 2.0
	v_fma_f32 v190, -v190, v167, 2.0
	v_mul_f32_e32 v166, v166, v189
	v_mul_f32_e32 v167, v167, v190
	v_mul_f32_e32 v182, v182, v166
	v_mul_f32_e32 v183, v183, v167
	v_rcp_f32_e32 v166, v191
	v_rcp_f32_e32 v167, v192
	s_nop 0
	v_fma_f32 v191, -v191, v166, 2.0
	v_fma_f32 v192, -v192, v167, 2.0
	v_mul_f32_e32 v166, v166, v191
	v_mul_f32_e32 v167, v167, v192
	v_mul_f32_e32 v184, v184, v166
	v_mul_f32_e32 v185, v185, v167
	v_mul_f32_e32 v68, v182, v68
	v_mul_f32_e32 v69, v183, v69
	v_mul_f32_e32 v70, v184, v70
	v_mul_f32_e32 v71, v185, v71
	v_cvt_pk_bf16_f32 v68, v68, v69
	v_cvt_pk_bf16_f32 v69, v70, v71
	ds_write_b64 v160, v[68:69] offset:208
	ds_read_b64 v[164:165], v160 offset:224
	s_waitcnt vmcnt(1) lgkmcnt(0)
	v_lshlrev_b32_e32 v182, 16, v164
	v_and_b32_e32 v183, 0xffff0000, v164
	v_lshlrev_b32_e32 v184, 16, v165
	v_and_b32_e32 v185, 0xffff0000, v165
	v_add_f32_e32 v72, v136, v72
	v_mul_f32_e32 v72, v152, v72
	v_add_f32_e32 v73, v137, v73
	v_mul_f32_e32 v73, v153, v73
	v_add_f32_e32 v74, v138, v74
	v_mul_f32_e32 v74, v154, v74
	v_add_f32_e32 v75, v139, v75
	v_mul_f32_e32 v75, v155, v75
	v_mul_f32_e32 v189, 0xbfb8aa3b, v182
	v_mul_f32_e32 v190, 0xbfb8aa3b, v183
	v_mul_f32_e32 v191, 0xbfb8aa3b, v184
	v_mul_f32_e32 v192, 0xbfb8aa3b, v185
	v_exp_f32_e32 v189, v189
	v_exp_f32_e32 v190, v190
	v_exp_f32_e32 v191, v191
	v_exp_f32_e32 v192, v192
	s_nop 0
	v_add_f32_e32 v189, 1.0, v189
	v_add_f32_e32 v190, 1.0, v190
	v_add_f32_e32 v191, 1.0, v191
	v_add_f32_e32 v192, 1.0, v192
	v_rcp_f32_e32 v166, v189
	v_rcp_f32_e32 v167, v190
	s_nop 0
	v_fma_f32 v189, -v189, v166, 2.0
	v_fma_f32 v190, -v190, v167, 2.0
	v_mul_f32_e32 v166, v166, v189
	v_mul_f32_e32 v167, v167, v190
	v_mul_f32_e32 v182, v182, v166
	v_mul_f32_e32 v183, v183, v167
	v_rcp_f32_e32 v166, v191
	v_rcp_f32_e32 v167, v192
	s_nop 0
	v_fma_f32 v191, -v191, v166, 2.0
	v_fma_f32 v192, -v192, v167, 2.0
	v_mul_f32_e32 v166, v166, v191
	v_mul_f32_e32 v167, v167, v192
	v_mul_f32_e32 v184, v184, v166
	v_mul_f32_e32 v185, v185, v167
	v_mul_f32_e32 v72, v182, v72
	v_mul_f32_e32 v73, v183, v73
	v_mul_f32_e32 v74, v184, v74
	v_mul_f32_e32 v75, v185, v75
	v_cvt_pk_bf16_f32 v72, v72, v73
	v_cvt_pk_bf16_f32 v73, v74, v75
	ds_write_b64 v160, v[72:73] offset:224
	ds_read_b64 v[164:165], v160 offset:240
	s_waitcnt vmcnt(0) lgkmcnt(0)
	v_lshlrev_b32_e32 v182, 16, v164
	v_and_b32_e32 v183, 0xffff0000, v164
	v_lshlrev_b32_e32 v184, 16, v165
	v_and_b32_e32 v185, 0xffff0000, v165
	v_add_f32_e32 v76, v140, v76
	v_mul_f32_e32 v76, v156, v76
	v_add_f32_e32 v77, v141, v77
	v_mul_f32_e32 v77, v157, v77
	v_add_f32_e32 v78, v142, v78
	v_mul_f32_e32 v78, v158, v78
	v_add_f32_e32 v79, v143, v79
	v_mul_f32_e32 v79, v159, v79
	v_mul_f32_e32 v189, 0xbfb8aa3b, v182
	v_mul_f32_e32 v190, 0xbfb8aa3b, v183
	v_mul_f32_e32 v191, 0xbfb8aa3b, v184
	v_mul_f32_e32 v192, 0xbfb8aa3b, v185
	v_exp_f32_e32 v189, v189
	v_exp_f32_e32 v190, v190
	v_exp_f32_e32 v191, v191
	v_exp_f32_e32 v192, v192
	s_nop 0
	v_add_f32_e32 v189, 1.0, v189
	v_add_f32_e32 v190, 1.0, v190
	v_add_f32_e32 v191, 1.0, v191
	v_add_f32_e32 v192, 1.0, v192
	v_rcp_f32_e32 v166, v189
	v_rcp_f32_e32 v167, v190
	s_nop 0
	v_fma_f32 v189, -v189, v166, 2.0
	v_fma_f32 v190, -v190, v167, 2.0
	v_mul_f32_e32 v166, v166, v189
	v_mul_f32_e32 v167, v167, v190
	v_mul_f32_e32 v182, v182, v166
	v_mul_f32_e32 v183, v183, v167
	v_rcp_f32_e32 v166, v191
	v_rcp_f32_e32 v167, v192
	s_nop 0
	v_fma_f32 v191, -v191, v166, 2.0
	v_fma_f32 v192, -v192, v167, 2.0
	v_mul_f32_e32 v166, v166, v191
	v_mul_f32_e32 v167, v167, v192
	v_mul_f32_e32 v184, v184, v166
	v_mul_f32_e32 v185, v185, v167
	v_mul_f32_e32 v76, v182, v76
	v_mul_f32_e32 v77, v183, v77
	v_mul_f32_e32 v78, v184, v78
	v_mul_f32_e32 v79, v185, v79
	v_cvt_pk_bf16_f32 v76, v76, v77
	v_cvt_pk_bf16_f32 v77, v78, v79
	ds_write_b64 v160, v[76:77] offset:240
	s_waitcnt lgkmcnt(0)
; DI bfr f2bf(float a) { return (bfr)(pack2(a, 0.f) & 0xffffu); }
; DI float bf2f(bfr u) { return __uint_as_float(((unsigned)u) << 16); }
; DI float siluf_(float x) { return x / (1.0f + __expf(-x)); }
; DI void phase_gemm_pool(const Params& p, char* smem) {
;     ...
;     gemm_tile<1024>(p.MIX + g * 256, p.WtPool + (size_t)g * 65536, 256, 256, mt * 128, nt * 256, smem,
;               [=](int row, int col, float v) {
;                 float gate = bf2f(P2[(size_t)row * 2048 + 1024 + g * 256 + col]);
;                 float z = (v + bp[col]) * sc[col] * siluf_(gate);
;                 Z[(size_t)row * 1024 + g * 256 + col] = f2bf(z);
;               });
	ds_read_b128 v[128:131], v162
	ds_read_b128 v[132:135], v162 offset:1088
	ds_read_b128 v[136:139], v162 offset:2176
	ds_read_b128 v[140:143], v162 offset:3264
	ds_read_b128 v[144:147], v162 offset:4352
	ds_read_b128 v[148:151], v162 offset:5440
	ds_read_b128 v[152:155], v162 offset:6528
	ds_read_b128 v[156:159], v162 offset:7616
	s_add_u32 s74, s66, 0x0
	s_addc_u32 s75, s67, 0
	s_waitcnt lgkmcnt(7)
	global_store_dwordx4 v180, v[128:131], s[74:75]
	s_add_u32 s74, s66, 0x2000
	s_addc_u32 s75, s67, 0
	s_waitcnt lgkmcnt(6)
	global_store_dwordx4 v180, v[132:135], s[74:75]
	s_add_u32 s74, s66, 0x4000
	s_addc_u32 s75, s67, 0
	s_waitcnt lgkmcnt(5)
	global_store_dwordx4 v180, v[136:139], s[74:75]
	s_add_u32 s74, s66, 0x6000
	s_addc_u32 s75, s67, 0
	s_waitcnt lgkmcnt(4)
	global_store_dwordx4 v180, v[140:143], s[74:75]
	s_add_u32 s74, s66, 0x8000
	s_addc_u32 s75, s67, 0
	s_waitcnt lgkmcnt(3)
	global_store_dwordx4 v180, v[144:147], s[74:75]
	s_add_u32 s74, s66, 0xa000
	s_addc_u32 s75, s67, 0
	s_waitcnt lgkmcnt(2)
	global_store_dwordx4 v180, v[148:151], s[74:75]
	s_add_u32 s74, s66, 0xc000
	s_addc_u32 s75, s67, 0
	s_waitcnt lgkmcnt(1)
	global_store_dwordx4 v180, v[152:155], s[74:75]
	s_add_u32 s74, s66, 0xe000
	s_addc_u32 s75, s67, 0
	s_waitcnt lgkmcnt(0)
	global_store_dwordx4 v180, v[156:159], s[74:75]
	s_add_u32 s74, s64, 0x20000
	s_addc_u32 s75, s65, 0
	global_load_dwordx4 v[128:131], v163, s[74:75]
	s_add_u32 s74, s64, 0x24000
	s_addc_u32 s75, s65, 0
	global_load_dwordx4 v[132:135], v163, s[74:75]
	s_add_u32 s74, s64, 0x28000
	s_addc_u32 s75, s65, 0
	global_load_dwordx4 v[136:139], v163, s[74:75]
	s_add_u32 s74, s64, 0x2c000
	s_addc_u32 s75, s65, 0
	global_load_dwordx4 v[140:143], v163, s[74:75]
	s_add_u32 s74, s64, 0x30000
	s_addc_u32 s75, s65, 0
	global_load_dwordx4 v[144:147], v163, s[74:75]
	s_add_u32 s74, s64, 0x34000
	s_addc_u32 s75, s65, 0
	global_load_dwordx4 v[148:151], v163, s[74:75]
	s_add_u32 s74, s64, 0x38000
	s_addc_u32 s75, s65, 0
	global_load_dwordx4 v[152:155], v163, s[74:75]
	s_add_u32 s74, s64, 0x3c000
	s_addc_u32 s75, s65, 0
	global_load_dwordx4 v[156:159], v163, s[74:75]
	s_waitcnt vmcnt(7)
	ds_write_b128 v162, v[128:131]
	s_waitcnt vmcnt(6)
	ds_write_b128 v162, v[132:135] offset:1088
	s_waitcnt vmcnt(5)
	ds_write_b128 v162, v[136:139] offset:2176
	s_waitcnt vmcnt(4)
	ds_write_b128 v162, v[140:143] offset:3264
	s_waitcnt vmcnt(3)
	ds_write_b128 v162, v[144:147] offset:4352
	s_waitcnt vmcnt(2)
	ds_write_b128 v162, v[148:151] offset:5440
	s_waitcnt vmcnt(1)
	ds_write_b128 v162, v[152:155] offset:6528
	s_waitcnt vmcnt(0)
	ds_write_b128 v162, v[156:159] offset:7616
	global_load_dwordx4 v[128:131], v181, s[68:69]
	global_load_dwordx4 v[132:135], v181, s[68:69] offset:32
	global_load_dwordx4 v[136:139], v181, s[68:69] offset:64
	global_load_dwordx4 v[140:143], v181, s[68:69] offset:96
	global_load_dwordx4 v[144:147], v181, s[70:71]
	global_load_dwordx4 v[148:151], v181, s[70:71] offset:32
	global_load_dwordx4 v[152:155], v181, s[70:71] offset:64
	global_load_dwordx4 v[156:159], v181, s[70:71] offset:96
	ds_read_b64 v[164:165], v160
	s_waitcnt vmcnt(3) lgkmcnt(0)
	v_lshlrev_b32_e32 v182, 16, v164
	v_and_b32_e32 v183, 0xffff0000, v164
	v_lshlrev_b32_e32 v184, 16, v165
	v_and_b32_e32 v185, 0xffff0000, v165
	v_add_f32_e32 v48, v128, v48
	v_mul_f32_e32 v48, v144, v48
	v_add_f32_e32 v49, v129, v49
	v_mul_f32_e32 v49, v145, v49
	v_add_f32_e32 v50, v130, v50
	v_mul_f32_e32 v50, v146, v50
	v_add_f32_e32 v51, v131, v51
	v_mul_f32_e32 v51, v147, v51
	v_mul_f32_e32 v189, 0xbfb8aa3b, v182
	v_mul_f32_e32 v190, 0xbfb8aa3b, v183
	v_mul_f32_e32 v191, 0xbfb8aa3b, v184
	v_mul_f32_e32 v192, 0xbfb8aa3b, v185
	v_exp_f32_e32 v189, v189
	v_exp_f32_e32 v190, v190
	v_exp_f32_e32 v191, v191
	v_exp_f32_e32 v192, v192
	s_nop 0
	v_add_f32_e32 v189, 1.0, v189
	v_add_f32_e32 v190, 1.0, v190
	v_add_f32_e32 v191, 1.0, v191
	v_add_f32_e32 v192, 1.0, v192
	v_rcp_f32_e32 v166, v189
	v_rcp_f32_e32 v167, v190
	s_nop 0
	v_fma_f32 v189, -v189, v166, 2.0
	v_fma_f32 v190, -v190, v167, 2.0
	v_mul_f32_e32 v166, v166, v189
	v_mul_f32_e32 v167, v167, v190
	v_mul_f32_e32 v182, v182, v166
	v_mul_f32_e32 v183, v183, v167
	v_rcp_f32_e32 v166, v191
	v_rcp_f32_e32 v167, v192
	s_nop 0
	v_fma_f32 v191, -v191, v166, 2.0
	v_fma_f32 v192, -v192, v167, 2.0
	v_mul_f32_e32 v166, v166, v191
	v_mul_f32_e32 v167, v167, v192
	v_mul_f32_e32 v184, v184, v166
	v_mul_f32_e32 v185, v185, v167
	v_mul_f32_e32 v48, v182, v48
	v_mul_f32_e32 v49, v183, v49
	v_mul_f32_e32 v50, v184, v50
	v_mul_f32_e32 v51, v185, v51
	v_cvt_pk_bf16_f32 v48, v48, v49
	v_cvt_pk_bf16_f32 v49, v50, v51
	ds_write_b64 v160, v[48:49]
	ds_read_b64 v[164:165], v160 offset:16
	s_waitcnt vmcnt(2) lgkmcnt(0)
	v_lshlrev_b32_e32 v182, 16, v164
	v_and_b32_e32 v183, 0xffff0000, v164
	v_lshlrev_b32_e32 v184, 16, v165
	v_and_b32_e32 v185, 0xffff0000, v165
	v_add_f32_e32 v52, v132, v52
	v_mul_f32_e32 v52, v148, v52
	v_add_f32_e32 v53, v133, v53
	v_mul_f32_e32 v53, v149, v53
	v_add_f32_e32 v54, v134, v54
	v_mul_f32_e32 v54, v150, v54
	v_add_f32_e32 v55, v135, v55
	v_mul_f32_e32 v55, v151, v55
	v_mul_f32_e32 v189, 0xbfb8aa3b, v182
	v_mul_f32_e32 v190, 0xbfb8aa3b, v183
	v_mul_f32_e32 v191, 0xbfb8aa3b, v184
	v_mul_f32_e32 v192, 0xbfb8aa3b, v185
	v_exp_f32_e32 v189, v189
	v_exp_f32_e32 v190, v190
	v_exp_f32_e32 v191, v191
	v_exp_f32_e32 v192, v192
	s_nop 0
	v_add_f32_e32 v189, 1.0, v189
	v_add_f32_e32 v190, 1.0, v190
	v_add_f32_e32 v191, 1.0, v191
	v_add_f32_e32 v192, 1.0, v192
	v_rcp_f32_e32 v166, v189
	v_rcp_f32_e32 v167, v190
	s_nop 0
	v_fma_f32 v189, -v189, v166, 2.0
	v_fma_f32 v190, -v190, v167, 2.0
	v_mul_f32_e32 v166, v166, v189
	v_mul_f32_e32 v167, v167, v190
	v_mul_f32_e32 v182, v182, v166
	v_mul_f32_e32 v183, v183, v167
	v_rcp_f32_e32 v166, v191
	v_rcp_f32_e32 v167, v192
	s_nop 0
	v_fma_f32 v191, -v191, v166, 2.0
	v_fma_f32 v192, -v192, v167, 2.0
	v_mul_f32_e32 v166, v166, v191
	v_mul_f32_e32 v167, v167, v192
	v_mul_f32_e32 v184, v184, v166
	v_mul_f32_e32 v185, v185, v167
	v_mul_f32_e32 v52, v182, v52
	v_mul_f32_e32 v53, v183, v53
	v_mul_f32_e32 v54, v184, v54
	v_mul_f32_e32 v55, v185, v55
	v_cvt_pk_bf16_f32 v52, v52, v53
	v_cvt_pk_bf16_f32 v53, v54, v55
	ds_write_b64 v160, v[52:53] offset:16
	ds_read_b64 v[164:165], v160 offset:32
	s_waitcnt vmcnt(1) lgkmcnt(0)
; DI bfr f2bf(float a) { return (bfr)(pack2(a, 0.f) & 0xffffu); }
; DI float bf2f(bfr u) { return __uint_as_float(((unsigned)u) << 16); }
; DI float siluf_(float x) { return x / (1.0f + __expf(-x)); }
; DI void phase_gemm_pool(const Params& p, char* smem) {
;     ...
;                 float gate = bf2f(P2[(size_t)row * 2048 + 1024 + g * 256 + col]);
;                 float z = (v + bp[col]) * sc[col] * siluf_(gate);
;                 Z[(size_t)row * 1024 + g * 256 + col] = f2bf(z);
	v_lshlrev_b32_e32 v182, 16, v164
	v_and_b32_e32 v183, 0xffff0000, v164
	v_lshlrev_b32_e32 v184, 16, v165
	v_and_b32_e32 v185, 0xffff0000, v165
	v_add_f32_e32 v56, v136, v56
	v_mul_f32_e32 v56, v152, v56
	v_add_f32_e32 v57, v137, v57
	v_mul_f32_e32 v57, v153, v57
	v_add_f32_e32 v58, v138, v58
	v_mul_f32_e32 v58, v154, v58
	v_add_f32_e32 v59, v139, v59
	v_mul_f32_e32 v59, v155, v59
	v_mul_f32_e32 v189, 0xbfb8aa3b, v182
	v_mul_f32_e32 v190, 0xbfb8aa3b, v183
	v_mul_f32_e32 v191, 0xbfb8aa3b, v184
	v_mul_f32_e32 v192, 0xbfb8aa3b, v185
	v_exp_f32_e32 v189, v189
	v_exp_f32_e32 v190, v190
	v_exp_f32_e32 v191, v191
	v_exp_f32_e32 v192, v192
	s_nop 0
	v_add_f32_e32 v189, 1.0, v189
	v_add_f32_e32 v190, 1.0, v190
	v_add_f32_e32 v191, 1.0, v191
	v_add_f32_e32 v192, 1.0, v192
	v_rcp_f32_e32 v166, v189
	v_rcp_f32_e32 v167, v190
	s_nop 0
	v_fma_f32 v189, -v189, v166, 2.0
	v_fma_f32 v190, -v190, v167, 2.0
	v_mul_f32_e32 v166, v166, v189
	v_mul_f32_e32 v167, v167, v190
	v_mul_f32_e32 v182, v182, v166
	v_mul_f32_e32 v183, v183, v167
	v_rcp_f32_e32 v166, v191
	v_rcp_f32_e32 v167, v192
	s_nop 0
	v_fma_f32 v191, -v191, v166, 2.0
	v_fma_f32 v192, -v192, v167, 2.0
	v_mul_f32_e32 v166, v166, v191
	v_mul_f32_e32 v167, v167, v192
	v_mul_f32_e32 v184, v184, v166
	v_mul_f32_e32 v185, v185, v167
	v_mul_f32_e32 v56, v182, v56
	v_mul_f32_e32 v57, v183, v57
	v_mul_f32_e32 v58, v184, v58
	v_mul_f32_e32 v59, v185, v59
	v_cvt_pk_bf16_f32 v56, v56, v57
	v_cvt_pk_bf16_f32 v57, v58, v59
	ds_write_b64 v160, v[56:57] offset:32
	ds_read_b64 v[164:165], v160 offset:48
	s_waitcnt vmcnt(0) lgkmcnt(0)
	v_lshlrev_b32_e32 v182, 16, v164
	v_and_b32_e32 v183, 0xffff0000, v164
	v_lshlrev_b32_e32 v184, 16, v165
	v_and_b32_e32 v185, 0xffff0000, v165
	v_add_f32_e32 v60, v140, v60
	v_mul_f32_e32 v60, v156, v60
	v_add_f32_e32 v61, v141, v61
	v_mul_f32_e32 v61, v157, v61
	v_add_f32_e32 v62, v142, v62
	v_mul_f32_e32 v62, v158, v62
	v_add_f32_e32 v63, v143, v63
	v_mul_f32_e32 v63, v159, v63
	v_mul_f32_e32 v189, 0xbfb8aa3b, v182
	v_mul_f32_e32 v190, 0xbfb8aa3b, v183
	v_mul_f32_e32 v191, 0xbfb8aa3b, v184
	v_mul_f32_e32 v192, 0xbfb8aa3b, v185
	v_exp_f32_e32 v189, v189
	v_exp_f32_e32 v190, v190
	v_exp_f32_e32 v191, v191
	v_exp_f32_e32 v192, v192
	s_nop 0
	v_add_f32_e32 v189, 1.0, v189
	v_add_f32_e32 v190, 1.0, v190
	v_add_f32_e32 v191, 1.0, v191
	v_add_f32_e32 v192, 1.0, v192
	v_rcp_f32_e32 v166, v189
	v_rcp_f32_e32 v167, v190
	s_nop 0
	v_fma_f32 v189, -v189, v166, 2.0
	v_fma_f32 v190, -v190, v167, 2.0
	v_mul_f32_e32 v166, v166, v189
	v_mul_f32_e32 v167, v167, v190
	v_mul_f32_e32 v182, v182, v166
	v_mul_f32_e32 v183, v183, v167
	v_rcp_f32_e32 v166, v191
	v_rcp_f32_e32 v167, v192
	s_nop 0
	v_fma_f32 v191, -v191, v166, 2.0
	v_fma_f32 v192, -v192, v167, 2.0
	v_mul_f32_e32 v166, v166, v191
	v_mul_f32_e32 v167, v167, v192
	v_mul_f32_e32 v184, v184, v166
	v_mul_f32_e32 v185, v185, v167
	v_mul_f32_e32 v60, v182, v60
	v_mul_f32_e32 v61, v183, v61
	v_mul_f32_e32 v62, v184, v62
	v_mul_f32_e32 v63, v185, v63
	v_cvt_pk_bf16_f32 v60, v60, v61
	v_cvt_pk_bf16_f32 v61, v62, v63
	ds_write_b64 v160, v[60:61] offset:48
	global_load_dwordx4 v[128:131], v181, s[68:69] offset:128
	global_load_dwordx4 v[132:135], v181, s[68:69] offset:160
	global_load_dwordx4 v[136:139], v181, s[68:69] offset:192
	global_load_dwordx4 v[140:143], v181, s[68:69] offset:224
	global_load_dwordx4 v[144:147], v181, s[70:71] offset:128
	global_load_dwordx4 v[148:151], v181, s[70:71] offset:160
	global_load_dwordx4 v[152:155], v181, s[70:71] offset:192
	global_load_dwordx4 v[156:159], v181, s[70:71] offset:224
	ds_read_b64 v[164:165], v160 offset:64
	s_waitcnt vmcnt(3) lgkmcnt(0)
	v_lshlrev_b32_e32 v182, 16, v164
	v_and_b32_e32 v183, 0xffff0000, v164
	v_lshlrev_b32_e32 v184, 16, v165
	v_and_b32_e32 v185, 0xffff0000, v165
	v_add_f32_e32 v32, v128, v32
	v_mul_f32_e32 v32, v144, v32
	v_add_f32_e32 v33, v129, v33
	v_mul_f32_e32 v33, v145, v33
	v_add_f32_e32 v34, v130, v34
	v_mul_f32_e32 v34, v146, v34
	v_add_f32_e32 v35, v131, v35
	v_mul_f32_e32 v35, v147, v35
	v_mul_f32_e32 v189, 0xbfb8aa3b, v182
	v_mul_f32_e32 v190, 0xbfb8aa3b, v183
	v_mul_f32_e32 v191, 0xbfb8aa3b, v184
	v_mul_f32_e32 v192, 0xbfb8aa3b, v185
	v_exp_f32_e32 v189, v189
	v_exp_f32_e32 v190, v190
	v_exp_f32_e32 v191, v191
	v_exp_f32_e32 v192, v192
	s_nop 0
	v_add_f32_e32 v189, 1.0, v189
	v_add_f32_e32 v190, 1.0, v190
	v_add_f32_e32 v191, 1.0, v191
	v_add_f32_e32 v192, 1.0, v192
	v_rcp_f32_e32 v166, v189
	v_rcp_f32_e32 v167, v190
	s_nop 0
	v_fma_f32 v189, -v189, v166, 2.0
	v_fma_f32 v190, -v190, v167, 2.0
	v_mul_f32_e32 v166, v166, v189
	v_mul_f32_e32 v167, v167, v190
	v_mul_f32_e32 v182, v182, v166
	v_mul_f32_e32 v183, v183, v167
	v_rcp_f32_e32 v166, v191
	v_rcp_f32_e32 v167, v192
	s_nop 0
	v_fma_f32 v191, -v191, v166, 2.0
	v_fma_f32 v192, -v192, v167, 2.0
	v_mul_f32_e32 v166, v166, v191
	v_mul_f32_e32 v167, v167, v192
	v_mul_f32_e32 v184, v184, v166
	v_mul_f32_e32 v185, v185, v167
	v_mul_f32_e32 v32, v182, v32
	v_mul_f32_e32 v33, v183, v33
	v_mul_f32_e32 v34, v184, v34
	v_mul_f32_e32 v35, v185, v35
	v_cvt_pk_bf16_f32 v32, v32, v33
	v_cvt_pk_bf16_f32 v33, v34, v35
	ds_write_b64 v160, v[32:33] offset:64
	ds_read_b64 v[164:165], v160 offset:80
	s_waitcnt vmcnt(2) lgkmcnt(0)
; DI bfr f2bf(float a) { return (bfr)(pack2(a, 0.f) & 0xffffu); }
; DI float bf2f(bfr u) { return __uint_as_float(((unsigned)u) << 16); }
; DI float siluf_(float x) { return x / (1.0f + __expf(-x)); }
; DI void phase_gemm_pool(const Params& p, char* smem) {
;     ...
;                 float gate = bf2f(P2[(size_t)row * 2048 + 1024 + g * 256 + col]);
;                 float z = (v + bp[col]) * sc[col] * siluf_(gate);
;                 Z[(size_t)row * 1024 + g * 256 + col] = f2bf(z);
	v_lshlrev_b32_e32 v182, 16, v164
	v_and_b32_e32 v183, 0xffff0000, v164
	v_lshlrev_b32_e32 v184, 16, v165
	v_and_b32_e32 v185, 0xffff0000, v165
	v_add_f32_e32 v36, v132, v36
	v_mul_f32_e32 v36, v148, v36
	v_add_f32_e32 v37, v133, v37
	v_mul_f32_e32 v37, v149, v37
	v_add_f32_e32 v38, v134, v38
	v_mul_f32_e32 v38, v150, v38
	v_add_f32_e32 v39, v135, v39
	v_mul_f32_e32 v39, v151, v39
	v_mul_f32_e32 v189, 0xbfb8aa3b, v182
	v_mul_f32_e32 v190, 0xbfb8aa3b, v183
	v_mul_f32_e32 v191, 0xbfb8aa3b, v184
	v_mul_f32_e32 v192, 0xbfb8aa3b, v185
	v_exp_f32_e32 v189, v189
	v_exp_f32_e32 v190, v190
	v_exp_f32_e32 v191, v191
	v_exp_f32_e32 v192, v192
	s_nop 0
	v_add_f32_e32 v189, 1.0, v189
	v_add_f32_e32 v190, 1.0, v190
	v_add_f32_e32 v191, 1.0, v191
	v_add_f32_e32 v192, 1.0, v192
	v_rcp_f32_e32 v166, v189
	v_rcp_f32_e32 v167, v190
	s_nop 0
	v_fma_f32 v189, -v189, v166, 2.0
	v_fma_f32 v190, -v190, v167, 2.0
	v_mul_f32_e32 v166, v166, v189
	v_mul_f32_e32 v167, v167, v190
	v_mul_f32_e32 v182, v182, v166
	v_mul_f32_e32 v183, v183, v167
	v_rcp_f32_e32 v166, v191
	v_rcp_f32_e32 v167, v192
	s_nop 0
	v_fma_f32 v191, -v191, v166, 2.0
	v_fma_f32 v192, -v192, v167, 2.0
	v_mul_f32_e32 v166, v166, v191
	v_mul_f32_e32 v167, v167, v192
	v_mul_f32_e32 v184, v184, v166
	v_mul_f32_e32 v185, v185, v167
	v_mul_f32_e32 v36, v182, v36
	v_mul_f32_e32 v37, v183, v37
	v_mul_f32_e32 v38, v184, v38
	v_mul_f32_e32 v39, v185, v39
	v_cvt_pk_bf16_f32 v36, v36, v37
	v_cvt_pk_bf16_f32 v37, v38, v39
	ds_write_b64 v160, v[36:37] offset:80
	ds_read_b64 v[164:165], v160 offset:96
	s_waitcnt vmcnt(1) lgkmcnt(0)
	v_lshlrev_b32_e32 v182, 16, v164
	v_and_b32_e32 v183, 0xffff0000, v164
	v_lshlrev_b32_e32 v184, 16, v165
	v_and_b32_e32 v185, 0xffff0000, v165
	v_add_f32_e32 v40, v136, v40
	v_mul_f32_e32 v40, v152, v40
	v_add_f32_e32 v41, v137, v41
	v_mul_f32_e32 v41, v153, v41
	v_add_f32_e32 v42, v138, v42
	v_mul_f32_e32 v42, v154, v42
	v_add_f32_e32 v43, v139, v43
	v_mul_f32_e32 v43, v155, v43
	v_mul_f32_e32 v189, 0xbfb8aa3b, v182
	v_mul_f32_e32 v190, 0xbfb8aa3b, v183
	v_mul_f32_e32 v191, 0xbfb8aa3b, v184
	v_mul_f32_e32 v192, 0xbfb8aa3b, v185
	v_exp_f32_e32 v189, v189
	v_exp_f32_e32 v190, v190
	v_exp_f32_e32 v191, v191
	v_exp_f32_e32 v192, v192
	s_nop 0
	v_add_f32_e32 v189, 1.0, v189
	v_add_f32_e32 v190, 1.0, v190
	v_add_f32_e32 v191, 1.0, v191
	v_add_f32_e32 v192, 1.0, v192
	v_rcp_f32_e32 v166, v189
	v_rcp_f32_e32 v167, v190
	s_nop 0
	v_fma_f32 v189, -v189, v166, 2.0
	v_fma_f32 v190, -v190, v167, 2.0
	v_mul_f32_e32 v166, v166, v189
	v_mul_f32_e32 v167, v167, v190
	v_mul_f32_e32 v182, v182, v166
	v_mul_f32_e32 v183, v183, v167
	v_rcp_f32_e32 v166, v191
	v_rcp_f32_e32 v167, v192
	s_nop 0
	v_fma_f32 v191, -v191, v166, 2.0
	v_fma_f32 v192, -v192, v167, 2.0
	v_mul_f32_e32 v166, v166, v191
	v_mul_f32_e32 v167, v167, v192
	v_mul_f32_e32 v184, v184, v166
	v_mul_f32_e32 v185, v185, v167
	v_mul_f32_e32 v40, v182, v40
	v_mul_f32_e32 v41, v183, v41
	v_mul_f32_e32 v42, v184, v42
	v_mul_f32_e32 v43, v185, v43
	v_cvt_pk_bf16_f32 v40, v40, v41
	v_cvt_pk_bf16_f32 v41, v42, v43
	ds_write_b64 v160, v[40:41] offset:96
	ds_read_b64 v[164:165], v160 offset:112
	s_waitcnt vmcnt(0) lgkmcnt(0)
	v_lshlrev_b32_e32 v182, 16, v164
	v_and_b32_e32 v183, 0xffff0000, v164
	v_lshlrev_b32_e32 v184, 16, v165
	v_and_b32_e32 v185, 0xffff0000, v165
	v_add_f32_e32 v44, v140, v44
	v_mul_f32_e32 v44, v156, v44
	v_add_f32_e32 v45, v141, v45
	v_mul_f32_e32 v45, v157, v45
	v_add_f32_e32 v46, v142, v46
	v_mul_f32_e32 v46, v158, v46
	v_add_f32_e32 v47, v143, v47
	v_mul_f32_e32 v47, v159, v47
	v_mul_f32_e32 v189, 0xbfb8aa3b, v182
	v_mul_f32_e32 v190, 0xbfb8aa3b, v183
	v_mul_f32_e32 v191, 0xbfb8aa3b, v184
	v_mul_f32_e32 v192, 0xbfb8aa3b, v185
	v_exp_f32_e32 v189, v189
	v_exp_f32_e32 v190, v190
	v_exp_f32_e32 v191, v191
	v_exp_f32_e32 v192, v192
	s_nop 0
	v_add_f32_e32 v189, 1.0, v189
	v_add_f32_e32 v190, 1.0, v190
	v_add_f32_e32 v191, 1.0, v191
	v_add_f32_e32 v192, 1.0, v192
	v_rcp_f32_e32 v166, v189
	v_rcp_f32_e32 v167, v190
	s_nop 0
	v_fma_f32 v189, -v189, v166, 2.0
	v_fma_f32 v190, -v190, v167, 2.0
	v_mul_f32_e32 v166, v166, v189
	v_mul_f32_e32 v167, v167, v190
	v_mul_f32_e32 v182, v182, v166
	v_mul_f32_e32 v183, v183, v167
	v_rcp_f32_e32 v166, v191
	v_rcp_f32_e32 v167, v192
	s_nop 0
	v_fma_f32 v191, -v191, v166, 2.0
	v_fma_f32 v192, -v192, v167, 2.0
	v_mul_f32_e32 v166, v166, v191
	v_mul_f32_e32 v167, v167, v192
	v_mul_f32_e32 v184, v184, v166
	v_mul_f32_e32 v185, v185, v167
	v_mul_f32_e32 v44, v182, v44
	v_mul_f32_e32 v45, v183, v45
	v_mul_f32_e32 v46, v184, v46
	v_mul_f32_e32 v47, v185, v47
	v_cvt_pk_bf16_f32 v44, v44, v45
	v_cvt_pk_bf16_f32 v45, v46, v47
	ds_write_b64 v160, v[44:45] offset:112
	global_load_dwordx4 v[128:131], v181, s[68:69] offset:256
	global_load_dwordx4 v[132:135], v181, s[68:69] offset:288
	global_load_dwordx4 v[136:139], v181, s[68:69] offset:320
	global_load_dwordx4 v[140:143], v181, s[68:69] offset:352
	global_load_dwordx4 v[144:147], v181, s[70:71] offset:256
	global_load_dwordx4 v[148:151], v181, s[70:71] offset:288
	global_load_dwordx4 v[152:155], v181, s[70:71] offset:320
	global_load_dwordx4 v[156:159], v181, s[70:71] offset:352
	ds_read_b64 v[164:165], v160 offset:128
	s_waitcnt vmcnt(3) lgkmcnt(0)
; DI bfr f2bf(float a) { return (bfr)(pack2(a, 0.f) & 0xffffu); }
; DI float bf2f(bfr u) { return __uint_as_float(((unsigned)u) << 16); }
; DI float siluf_(float x) { return x / (1.0f + __expf(-x)); }
; DI void phase_gemm_pool(const Params& p, char* smem) {
;     ...
;                 float gate = bf2f(P2[(size_t)row * 2048 + 1024 + g * 256 + col]);
;                 float z = (v + bp[col]) * sc[col] * siluf_(gate);
;                 Z[(size_t)row * 1024 + g * 256 + col] = f2bf(z);
	v_lshlrev_b32_e32 v182, 16, v164
	v_and_b32_e32 v183, 0xffff0000, v164
	v_lshlrev_b32_e32 v184, 16, v165
	v_and_b32_e32 v185, 0xffff0000, v165
	v_add_f32_e32 v16, v128, v16
	v_mul_f32_e32 v16, v144, v16
	v_add_f32_e32 v17, v129, v17
	v_mul_f32_e32 v17, v145, v17
	v_add_f32_e32 v18, v130, v18
	v_mul_f32_e32 v18, v146, v18
	v_add_f32_e32 v19, v131, v19
	v_mul_f32_e32 v19, v147, v19
	v_mul_f32_e32 v189, 0xbfb8aa3b, v182
	v_mul_f32_e32 v190, 0xbfb8aa3b, v183
	v_mul_f32_e32 v191, 0xbfb8aa3b, v184
	v_mul_f32_e32 v192, 0xbfb8aa3b, v185
	v_exp_f32_e32 v189, v189
	v_exp_f32_e32 v190, v190
	v_exp_f32_e32 v191, v191
	v_exp_f32_e32 v192, v192
	s_nop 0
	v_add_f32_e32 v189, 1.0, v189
	v_add_f32_e32 v190, 1.0, v190
	v_add_f32_e32 v191, 1.0, v191
	v_add_f32_e32 v192, 1.0, v192
	v_rcp_f32_e32 v166, v189
	v_rcp_f32_e32 v167, v190
	s_nop 0
	v_fma_f32 v189, -v189, v166, 2.0
	v_fma_f32 v190, -v190, v167, 2.0
	v_mul_f32_e32 v166, v166, v189
	v_mul_f32_e32 v167, v167, v190
	v_mul_f32_e32 v182, v182, v166
	v_mul_f32_e32 v183, v183, v167
	v_rcp_f32_e32 v166, v191
	v_rcp_f32_e32 v167, v192
	s_nop 0
	v_fma_f32 v191, -v191, v166, 2.0
	v_fma_f32 v192, -v192, v167, 2.0
	v_mul_f32_e32 v166, v166, v191
	v_mul_f32_e32 v167, v167, v192
	v_mul_f32_e32 v184, v184, v166
	v_mul_f32_e32 v185, v185, v167
	v_mul_f32_e32 v16, v182, v16
	v_mul_f32_e32 v17, v183, v17
	v_mul_f32_e32 v18, v184, v18
	v_mul_f32_e32 v19, v185, v19
	v_cvt_pk_bf16_f32 v16, v16, v17
	v_cvt_pk_bf16_f32 v17, v18, v19
	ds_write_b64 v160, v[16:17] offset:128
	ds_read_b64 v[164:165], v160 offset:144
	s_waitcnt vmcnt(2) lgkmcnt(0)
	v_lshlrev_b32_e32 v182, 16, v164
	v_and_b32_e32 v183, 0xffff0000, v164
	v_lshlrev_b32_e32 v184, 16, v165
	v_and_b32_e32 v185, 0xffff0000, v165
	v_add_f32_e32 v20, v132, v20
	v_mul_f32_e32 v20, v148, v20
	v_add_f32_e32 v21, v133, v21
	v_mul_f32_e32 v21, v149, v21
	v_add_f32_e32 v22, v134, v22
	v_mul_f32_e32 v22, v150, v22
	v_add_f32_e32 v23, v135, v23
	v_mul_f32_e32 v23, v151, v23
	v_mul_f32_e32 v189, 0xbfb8aa3b, v182
	v_mul_f32_e32 v190, 0xbfb8aa3b, v183
	v_mul_f32_e32 v191, 0xbfb8aa3b, v184
	v_mul_f32_e32 v192, 0xbfb8aa3b, v185
	v_exp_f32_e32 v189, v189
	v_exp_f32_e32 v190, v190
	v_exp_f32_e32 v191, v191
	v_exp_f32_e32 v192, v192
	s_nop 0
	v_add_f32_e32 v189, 1.0, v189
	v_add_f32_e32 v190, 1.0, v190
	v_add_f32_e32 v191, 1.0, v191
	v_add_f32_e32 v192, 1.0, v192
	v_rcp_f32_e32 v166, v189
	v_rcp_f32_e32 v167, v190
	s_nop 0
	v_fma_f32 v189, -v189, v166, 2.0
	v_fma_f32 v190, -v190, v167, 2.0
	v_mul_f32_e32 v166, v166, v189
	v_mul_f32_e32 v167, v167, v190
	v_mul_f32_e32 v182, v182, v166
	v_mul_f32_e32 v183, v183, v167
	v_rcp_f32_e32 v166, v191
	v_rcp_f32_e32 v167, v192
	s_nop 0
	v_fma_f32 v191, -v191, v166, 2.0
	v_fma_f32 v192, -v192, v167, 2.0
	v_mul_f32_e32 v166, v166, v191
	v_mul_f32_e32 v167, v167, v192
	v_mul_f32_e32 v184, v184, v166
	v_mul_f32_e32 v185, v185, v167
	v_mul_f32_e32 v20, v182, v20
	v_mul_f32_e32 v21, v183, v21
	v_mul_f32_e32 v22, v184, v22
	v_mul_f32_e32 v23, v185, v23
	v_cvt_pk_bf16_f32 v20, v20, v21
	v_cvt_pk_bf16_f32 v21, v22, v23
	ds_write_b64 v160, v[20:21] offset:144
	ds_read_b64 v[164:165], v160 offset:160
	s_waitcnt vmcnt(1) lgkmcnt(0)
	v_lshlrev_b32_e32 v182, 16, v164
	v_and_b32_e32 v183, 0xffff0000, v164
	v_lshlrev_b32_e32 v184, 16, v165
	v_and_b32_e32 v185, 0xffff0000, v165
	v_add_f32_e32 v24, v136, v24
	v_mul_f32_e32 v24, v152, v24
	v_add_f32_e32 v25, v137, v25
	v_mul_f32_e32 v25, v153, v25
	v_add_f32_e32 v26, v138, v26
	v_mul_f32_e32 v26, v154, v26
	v_add_f32_e32 v27, v139, v27
	v_mul_f32_e32 v27, v155, v27
	v_mul_f32_e32 v189, 0xbfb8aa3b, v182
	v_mul_f32_e32 v190, 0xbfb8aa3b, v183
	v_mul_f32_e32 v191, 0xbfb8aa3b, v184
	v_mul_f32_e32 v192, 0xbfb8aa3b, v185
	v_exp_f32_e32 v189, v189
	v_exp_f32_e32 v190, v190
	v_exp_f32_e32 v191, v191
	v_exp_f32_e32 v192, v192
	s_nop 0
	v_add_f32_e32 v189, 1.0, v189
	v_add_f32_e32 v190, 1.0, v190
	v_add_f32_e32 v191, 1.0, v191
	v_add_f32_e32 v192, 1.0, v192
	v_rcp_f32_e32 v166, v189
	v_rcp_f32_e32 v167, v190
	s_nop 0
	v_fma_f32 v189, -v189, v166, 2.0
	v_fma_f32 v190, -v190, v167, 2.0
	v_mul_f32_e32 v166, v166, v189
	v_mul_f32_e32 v167, v167, v190
	v_mul_f32_e32 v182, v182, v166
	v_mul_f32_e32 v183, v183, v167
	v_rcp_f32_e32 v166, v191
	v_rcp_f32_e32 v167, v192
	s_nop 0
	v_fma_f32 v191, -v191, v166, 2.0
	v_fma_f32 v192, -v192, v167, 2.0
	v_mul_f32_e32 v166, v166, v191
	v_mul_f32_e32 v167, v167, v192
	v_mul_f32_e32 v184, v184, v166
	v_mul_f32_e32 v185, v185, v167
	v_mul_f32_e32 v24, v182, v24
	v_mul_f32_e32 v25, v183, v25
	v_mul_f32_e32 v26, v184, v26
	v_mul_f32_e32 v27, v185, v27
	v_cvt_pk_bf16_f32 v24, v24, v25
	v_cvt_pk_bf16_f32 v25, v26, v27
	ds_write_b64 v160, v[24:25] offset:160
	ds_read_b64 v[164:165], v160 offset:176
	s_waitcnt vmcnt(0) lgkmcnt(0)
; DI bfr f2bf(float a) { return (bfr)(pack2(a, 0.f) & 0xffffu); }
; DI float bf2f(bfr u) { return __uint_as_float(((unsigned)u) << 16); }
; DI float siluf_(float x) { return x / (1.0f + __expf(-x)); }
; DI void phase_gemm_pool(const Params& p, char* smem) {
;     ...
;                 float gate = bf2f(P2[(size_t)row * 2048 + 1024 + g * 256 + col]);
;                 float z = (v + bp[col]) * sc[col] * siluf_(gate);
;                 Z[(size_t)row * 1024 + g * 256 + col] = f2bf(z);
	v_lshlrev_b32_e32 v182, 16, v164
	v_and_b32_e32 v183, 0xffff0000, v164
	v_lshlrev_b32_e32 v184, 16, v165
	v_and_b32_e32 v185, 0xffff0000, v165
	v_add_f32_e32 v28, v140, v28
	v_mul_f32_e32 v28, v156, v28
	v_add_f32_e32 v29, v141, v29
	v_mul_f32_e32 v29, v157, v29
	v_add_f32_e32 v30, v142, v30
	v_mul_f32_e32 v30, v158, v30
	v_add_f32_e32 v31, v143, v31
	v_mul_f32_e32 v31, v159, v31
	v_mul_f32_e32 v189, 0xbfb8aa3b, v182
	v_mul_f32_e32 v190, 0xbfb8aa3b, v183
	v_mul_f32_e32 v191, 0xbfb8aa3b, v184
	v_mul_f32_e32 v192, 0xbfb8aa3b, v185
	v_exp_f32_e32 v189, v189
	v_exp_f32_e32 v190, v190
	v_exp_f32_e32 v191, v191
	v_exp_f32_e32 v192, v192
	s_nop 0
	v_add_f32_e32 v189, 1.0, v189
	v_add_f32_e32 v190, 1.0, v190
	v_add_f32_e32 v191, 1.0, v191
	v_add_f32_e32 v192, 1.0, v192
	v_rcp_f32_e32 v166, v189
	v_rcp_f32_e32 v167, v190
	s_nop 0
	v_fma_f32 v189, -v189, v166, 2.0
	v_fma_f32 v190, -v190, v167, 2.0
	v_mul_f32_e32 v166, v166, v189
	v_mul_f32_e32 v167, v167, v190
	v_mul_f32_e32 v182, v182, v166
	v_mul_f32_e32 v183, v183, v167
	v_rcp_f32_e32 v166, v191
	v_rcp_f32_e32 v167, v192
	s_nop 0
	v_fma_f32 v191, -v191, v166, 2.0
	v_fma_f32 v192, -v192, v167, 2.0
	v_mul_f32_e32 v166, v166, v191
	v_mul_f32_e32 v167, v167, v192
	v_mul_f32_e32 v184, v184, v166
	v_mul_f32_e32 v185, v185, v167
	v_mul_f32_e32 v28, v182, v28
	v_mul_f32_e32 v29, v183, v29
	v_mul_f32_e32 v30, v184, v30
	v_mul_f32_e32 v31, v185, v31
	v_cvt_pk_bf16_f32 v28, v28, v29
	v_cvt_pk_bf16_f32 v29, v30, v31
	ds_write_b64 v160, v[28:29] offset:176
	global_load_dwordx4 v[128:131], v181, s[68:69] offset:384
	global_load_dwordx4 v[132:135], v181, s[68:69] offset:416
	global_load_dwordx4 v[136:139], v181, s[68:69] offset:448
	global_load_dwordx4 v[140:143], v181, s[68:69] offset:480
	global_load_dwordx4 v[144:147], v181, s[70:71] offset:384
	global_load_dwordx4 v[148:151], v181, s[70:71] offset:416
	global_load_dwordx4 v[152:155], v181, s[70:71] offset:448
	global_load_dwordx4 v[156:159], v181, s[70:71] offset:480
	ds_read_b64 v[164:165], v160 offset:192
	s_waitcnt vmcnt(3) lgkmcnt(0)
	v_lshlrev_b32_e32 v182, 16, v164
	v_and_b32_e32 v183, 0xffff0000, v164
	v_lshlrev_b32_e32 v184, 16, v165
	v_and_b32_e32 v185, 0xffff0000, v165
	v_add_f32_e32 v0, v128, v0
	v_mul_f32_e32 v0, v144, v0
	v_add_f32_e32 v1, v129, v1
	v_mul_f32_e32 v1, v145, v1
	v_add_f32_e32 v2, v130, v2
	v_mul_f32_e32 v2, v146, v2
	v_add_f32_e32 v3, v131, v3
	v_mul_f32_e32 v3, v147, v3
	v_mul_f32_e32 v189, 0xbfb8aa3b, v182
	v_mul_f32_e32 v190, 0xbfb8aa3b, v183
	v_mul_f32_e32 v191, 0xbfb8aa3b, v184
	v_mul_f32_e32 v192, 0xbfb8aa3b, v185
	v_exp_f32_e32 v189, v189
	v_exp_f32_e32 v190, v190
	v_exp_f32_e32 v191, v191
	v_exp_f32_e32 v192, v192
	s_nop 0
	v_add_f32_e32 v189, 1.0, v189
	v_add_f32_e32 v190, 1.0, v190
	v_add_f32_e32 v191, 1.0, v191
	v_add_f32_e32 v192, 1.0, v192
	v_rcp_f32_e32 v166, v189
	v_rcp_f32_e32 v167, v190
	s_nop 0
	v_fma_f32 v189, -v189, v166, 2.0
	v_fma_f32 v190, -v190, v167, 2.0
	v_mul_f32_e32 v166, v166, v189
	v_mul_f32_e32 v167, v167, v190
	v_mul_f32_e32 v182, v182, v166
	v_mul_f32_e32 v183, v183, v167
	v_rcp_f32_e32 v166, v191
	v_rcp_f32_e32 v167, v192
	s_nop 0
	v_fma_f32 v191, -v191, v166, 2.0
	v_fma_f32 v192, -v192, v167, 2.0
	v_mul_f32_e32 v166, v166, v191
	v_mul_f32_e32 v167, v167, v192
	v_mul_f32_e32 v184, v184, v166
	v_mul_f32_e32 v185, v185, v167
	v_mul_f32_e32 v0, v182, v0
	v_mul_f32_e32 v1, v183, v1
	v_mul_f32_e32 v2, v184, v2
	v_mul_f32_e32 v3, v185, v3
	v_cvt_pk_bf16_f32 v0, v0, v1
	v_cvt_pk_bf16_f32 v1, v2, v3
	ds_write_b64 v160, v[0:1] offset:192
	ds_read_b64 v[164:165], v160 offset:208
	s_waitcnt vmcnt(2) lgkmcnt(0)
	v_lshlrev_b32_e32 v182, 16, v164
	v_and_b32_e32 v183, 0xffff0000, v164
	v_lshlrev_b32_e32 v184, 16, v165
	v_and_b32_e32 v185, 0xffff0000, v165
	v_add_f32_e32 v4, v132, v4
	v_mul_f32_e32 v4, v148, v4
	v_add_f32_e32 v5, v133, v5
	v_mul_f32_e32 v5, v149, v5
	v_add_f32_e32 v6, v134, v6
	v_mul_f32_e32 v6, v150, v6
	v_add_f32_e32 v7, v135, v7
	v_mul_f32_e32 v7, v151, v7
	v_mul_f32_e32 v189, 0xbfb8aa3b, v182
	v_mul_f32_e32 v190, 0xbfb8aa3b, v183
	v_mul_f32_e32 v191, 0xbfb8aa3b, v184
	v_mul_f32_e32 v192, 0xbfb8aa3b, v185
	v_exp_f32_e32 v189, v189
	v_exp_f32_e32 v190, v190
	v_exp_f32_e32 v191, v191
	v_exp_f32_e32 v192, v192
	s_nop 0
	v_add_f32_e32 v189, 1.0, v189
	v_add_f32_e32 v190, 1.0, v190
	v_add_f32_e32 v191, 1.0, v191
	v_add_f32_e32 v192, 1.0, v192
	v_rcp_f32_e32 v166, v189
	v_rcp_f32_e32 v167, v190
	s_nop 0
	v_fma_f32 v189, -v189, v166, 2.0
	v_fma_f32 v190, -v190, v167, 2.0
	v_mul_f32_e32 v166, v166, v189
	v_mul_f32_e32 v167, v167, v190
	v_mul_f32_e32 v182, v182, v166
	v_mul_f32_e32 v183, v183, v167
	v_rcp_f32_e32 v166, v191
	v_rcp_f32_e32 v167, v192
	s_nop 0
	v_fma_f32 v191, -v191, v166, 2.0
	v_fma_f32 v192, -v192, v167, 2.0
	v_mul_f32_e32 v166, v166, v191
	v_mul_f32_e32 v167, v167, v192
	v_mul_f32_e32 v184, v184, v166
	v_mul_f32_e32 v185, v185, v167
	v_mul_f32_e32 v4, v182, v4
	v_mul_f32_e32 v5, v183, v5
	v_mul_f32_e32 v6, v184, v6
	v_mul_f32_e32 v7, v185, v7
	v_cvt_pk_bf16_f32 v4, v4, v5
	v_cvt_pk_bf16_f32 v5, v6, v7
	ds_write_b64 v160, v[4:5] offset:208
	ds_read_b64 v[164:165], v160 offset:224
	s_waitcnt vmcnt(1) lgkmcnt(0)
; DI bfr f2bf(float a) { return (bfr)(pack2(a, 0.f) & 0xffffu); }
; DI float bf2f(bfr u) { return __uint_as_float(((unsigned)u) << 16); }
; DI float siluf_(float x) { return x / (1.0f + __expf(-x)); }
; DI void phase_gemm_pool(const Params& p, char* smem) {
;     ...
;   for (int t0 = blockIdx.x; t0 < 128 * 4; t0 += gridDim.x) {
;     const int t = ((gridDim.x & 7) == 0) ? xcd_tile(t0, 4) : t0;
;     int mt = t >> 2, g = t & 3, nt = 0;
;     const float* bp = p.b_pool + g * 256;
;     const float* sc = p.pool_scale + g * 256;
;     gemm_tile<1024>(p.MIX + g * 256, p.WtPool + (size_t)g * 65536, 256, 256, mt * 128, nt * 256, smem,
;               [=](int row, int col, float v) {
;                 float gate = bf2f(P2[(size_t)row * 2048 + 1024 + g * 256 + col]);
;                 float z = (v + bp[col]) * sc[col] * siluf_(gate);
;                 Z[(size_t)row * 1024 + g * 256 + col] = f2bf(z);
;               });
;   }
	v_lshlrev_b32_e32 v182, 16, v164
	v_and_b32_e32 v183, 0xffff0000, v164
	v_lshlrev_b32_e32 v184, 16, v165
	v_and_b32_e32 v185, 0xffff0000, v165
	v_add_f32_e32 v8, v136, v8
	v_mul_f32_e32 v8, v152, v8
	v_add_f32_e32 v9, v137, v9
	v_mul_f32_e32 v9, v153, v9
	v_add_f32_e32 v10, v138, v10
	v_mul_f32_e32 v10, v154, v10
	v_add_f32_e32 v11, v139, v11
	v_mul_f32_e32 v11, v155, v11
	v_mul_f32_e32 v189, 0xbfb8aa3b, v182
	v_mul_f32_e32 v190, 0xbfb8aa3b, v183
	v_mul_f32_e32 v191, 0xbfb8aa3b, v184
	v_mul_f32_e32 v192, 0xbfb8aa3b, v185
	v_exp_f32_e32 v189, v189
	v_exp_f32_e32 v190, v190
	v_exp_f32_e32 v191, v191
	v_exp_f32_e32 v192, v192
	s_nop 0
	v_add_f32_e32 v189, 1.0, v189
	v_add_f32_e32 v190, 1.0, v190
	v_add_f32_e32 v191, 1.0, v191
	v_add_f32_e32 v192, 1.0, v192
	v_rcp_f32_e32 v166, v189
	v_rcp_f32_e32 v167, v190
	s_nop 0
	v_fma_f32 v189, -v189, v166, 2.0
	v_fma_f32 v190, -v190, v167, 2.0
	v_mul_f32_e32 v166, v166, v189
	v_mul_f32_e32 v167, v167, v190
	v_mul_f32_e32 v182, v182, v166
	v_mul_f32_e32 v183, v183, v167
	v_rcp_f32_e32 v166, v191
	v_rcp_f32_e32 v167, v192
	s_nop 0
	v_fma_f32 v191, -v191, v166, 2.0
	v_fma_f32 v192, -v192, v167, 2.0
	v_mul_f32_e32 v166, v166, v191
	v_mul_f32_e32 v167, v167, v192
	v_mul_f32_e32 v184, v184, v166
	v_mul_f32_e32 v185, v185, v167
	v_mul_f32_e32 v8, v182, v8
	v_mul_f32_e32 v9, v183, v9
	v_mul_f32_e32 v10, v184, v10
	v_mul_f32_e32 v11, v185, v11
	v_cvt_pk_bf16_f32 v8, v8, v9
	v_cvt_pk_bf16_f32 v9, v10, v11
	ds_write_b64 v160, v[8:9] offset:224
	ds_read_b64 v[164:165], v160 offset:240
	s_waitcnt vmcnt(0) lgkmcnt(0)
	v_lshlrev_b32_e32 v182, 16, v164
	v_and_b32_e32 v183, 0xffff0000, v164
	v_lshlrev_b32_e32 v184, 16, v165
	v_and_b32_e32 v185, 0xffff0000, v165
	v_add_f32_e32 v12, v140, v12
	v_mul_f32_e32 v12, v156, v12
	v_add_f32_e32 v13, v141, v13
	v_mul_f32_e32 v13, v157, v13
	v_add_f32_e32 v14, v142, v14
	v_mul_f32_e32 v14, v158, v14
	v_add_f32_e32 v15, v143, v15
	v_mul_f32_e32 v15, v159, v15
	v_mul_f32_e32 v189, 0xbfb8aa3b, v182
	v_mul_f32_e32 v190, 0xbfb8aa3b, v183
	v_mul_f32_e32 v191, 0xbfb8aa3b, v184
	v_mul_f32_e32 v192, 0xbfb8aa3b, v185
	v_exp_f32_e32 v189, v189
	v_exp_f32_e32 v190, v190
	v_exp_f32_e32 v191, v191
	v_exp_f32_e32 v192, v192
	s_nop 0
	v_add_f32_e32 v189, 1.0, v189
	v_add_f32_e32 v190, 1.0, v190
	v_add_f32_e32 v191, 1.0, v191
	v_add_f32_e32 v192, 1.0, v192
	v_rcp_f32_e32 v166, v189
	v_rcp_f32_e32 v167, v190
	s_nop 0
	v_fma_f32 v189, -v189, v166, 2.0
	v_fma_f32 v190, -v190, v167, 2.0
	v_mul_f32_e32 v166, v166, v189
	v_mul_f32_e32 v167, v167, v190
	v_mul_f32_e32 v182, v182, v166
	v_mul_f32_e32 v183, v183, v167
	v_rcp_f32_e32 v166, v191
	v_rcp_f32_e32 v167, v192
	s_nop 0
	v_fma_f32 v191, -v191, v166, 2.0
	v_fma_f32 v192, -v192, v167, 2.0
	v_mul_f32_e32 v166, v166, v191
	v_mul_f32_e32 v167, v167, v192
	v_mul_f32_e32 v184, v184, v166
	v_mul_f32_e32 v185, v185, v167
	v_mul_f32_e32 v12, v182, v12
	v_mul_f32_e32 v13, v183, v13
	v_mul_f32_e32 v14, v184, v14
	v_mul_f32_e32 v15, v185, v15
	v_cvt_pk_bf16_f32 v12, v12, v13
	v_cvt_pk_bf16_f32 v13, v14, v15
	ds_write_b64 v160, v[12:13] offset:240
	s_waitcnt lgkmcnt(0)
	ds_read_b128 v[128:131], v162
	ds_read_b128 v[132:135], v162 offset:1088
	ds_read_b128 v[136:139], v162 offset:2176
	ds_read_b128 v[140:143], v162 offset:3264
	ds_read_b128 v[144:147], v162 offset:4352
	ds_read_b128 v[148:151], v162 offset:5440
	ds_read_b128 v[152:155], v162 offset:6528
	ds_read_b128 v[156:159], v162 offset:7616
	s_add_u32 s74, s66, 0x10000
	s_addc_u32 s75, s67, 0
	s_waitcnt lgkmcnt(7)
	global_store_dwordx4 v180, v[128:131], s[74:75]
	s_add_u32 s74, s66, 0x12000
	s_addc_u32 s75, s67, 0
	s_waitcnt lgkmcnt(6)
	global_store_dwordx4 v180, v[132:135], s[74:75]
	s_add_u32 s74, s66, 0x14000
	s_addc_u32 s75, s67, 0
	s_waitcnt lgkmcnt(5)
	global_store_dwordx4 v180, v[136:139], s[74:75]
	s_add_u32 s74, s66, 0x16000
	s_addc_u32 s75, s67, 0
	s_waitcnt lgkmcnt(4)
	global_store_dwordx4 v180, v[140:143], s[74:75]
	s_add_u32 s74, s66, 0x18000
	s_addc_u32 s75, s67, 0
	s_waitcnt lgkmcnt(3)
	global_store_dwordx4 v180, v[144:147], s[74:75]
	s_add_u32 s74, s66, 0x1a000
	s_addc_u32 s75, s67, 0
	s_waitcnt lgkmcnt(2)
	global_store_dwordx4 v180, v[148:151], s[74:75]
	s_add_u32 s74, s66, 0x1c000
	s_addc_u32 s75, s67, 0
	s_waitcnt lgkmcnt(1)
	global_store_dwordx4 v180, v[152:155], s[74:75]
	s_add_u32 s74, s66, 0x1e000
	s_addc_u32 s75, s67, 0
	s_waitcnt lgkmcnt(0)
	global_store_dwordx4 v180, v[156:159], s[74:75]
	v_readlane_b32 s64, v188, 0
	v_readlane_b32 s65, v188, 1
	v_readlane_b32 s66, v188, 2
	v_readlane_b32 s67, v188, 3
	v_readlane_b32 s68, v188, 4
	v_readlane_b32 s69, v188, 5
	v_readlane_b32 s70, v188, 6
	v_readlane_b32 s71, v188, 7
	v_readlane_b32 s72, v188, 8
	v_readlane_b32 s73, v188, 9
	v_readlane_b32 s74, v188, 10
	v_readlane_b32 s75, v188, 11
	v_readlane_b32 s76, v188, 12
	v_readlane_b32 s77, v188, 13
	v_readlane_b32 s78, v188, 14
	v_readlane_b32 s79, v188, 15
	s_nop 7
	s_lshl_b32 s6, s22, 2
	s_add_u32 s4, s12, s6
	s_addc_u32 s5, s13, 0
	s_add_u32 s6, s14, s6
	s_addc_u32 s7, s15, 0
	s_lshl_b32 s10, s22, 1
	s_add_u32 s22, s16, s10
	s_addc_u32 s23, s17, 0
	s_add_i32 s37, s37, s24
	s_add_i32 s25, s25, s26
	s_cmpk_lt_i32 s37, 0x200
	s_cbranch_scc0 .LBB0_1395
	s_branch .LBB0_1377
